# hand-written attn_a phase (prefetch pipeline, table-masked bias) + batched bias lookups in mix_b2
# speedup vs baseline: 1.3045x; 1.3045x over previous
; #define LOADKV(BASECOL, SH) { _Pragma("unroll") for (int rr = 0; rr < 16; ++rr) { \
;       const unsigned vo_ = (unsigned)mySel[(SH) * 128 + rr * 8 + (lane >> 3)] * 4608u + (unsigned)(hkv * 128 + (lane & 7) * 16); \
;       vreg[rr] = *(const bf16x8*)((const char*)(Pb + (BASECOL)) + (size_t)vo_); } }
; #define KWRITE() { _Pragma("unroll") for (int rr = 0; rr < 16; ++rr) { const int row_ = rr * 8 + (lane >> 3), piece_ = lane & 7; \
;       *(bf16x8*)(Ks + row_ * 128 + ((piece_ ^ (row_ & 7)) * 16)) = vreg[rr]; } }
; #define LOADKV2(BASECOL, SH) { _Pragma("unroll") for (int rr = 0; rr < 16; ++rr) { \
;       const unsigned vo_ = (unsigned)mySel[(SH) * 128 + rr * 8 + (lane >> 3)] * 4608u + (unsigned)(hkv * 128 + (lane & 7) * 16); \
;       vreg2[rr] = *(const bf16x8*)((const char*)(Pb + (BASECOL)) + (size_t)vo_); } }
; #define KWRITE2() { _Pragma("unroll") for (int rr = 0; rr < 16; ++rr) { const int row_ = rr * 8 + (lane >> 3), piece_ = lane & 7; \
;       *(bf16x8*)(Ks + row_ * 128 + ((piece_ ^ (row_ & 7)) * 16)) = vreg2[rr]; } }
; DI void phase_mix_b2(int wv_, int vb_, int nvb_, char* ws_, const Ctx& p, char* smem) {
;     ...
;     bf16x8 vreg2[16];
;     ...
;     LOADKV(1024, 0)
;     LOADKV2(1024, 1)
;     asm volatile("s_waitcnt lgkmcnt(0)" ::: "memory");
;     KWRITE()
;     asm volatile("s_waitcnt lgkmcnt(0)" ::: "memory");
;     QKSTAGE(0)
;     asm volatile("s_waitcnt lgkmcnt(0)" ::: "memory");
;     KWRITE2()
.LBB0_355:
	s_or_b64 exec, exec, s[8:9]
	v_lshrrev_b32_e32 v127, 3, v221
	v_lshlrev_b32_e32 v224, 4, v220
	v_lshrrev_b32_e32 v223, 4, v10
	v_and_b32_e32 v10, 0x70, v224
	v_lshl_add_u32 v226, v127, 1, v11
	v_lshl_or_b32 v203, s12, 7, v10
	ds_read_u16 v10, v226
	ds_read_u16 v14, v226 offset:16
	ds_read_u16 v18, v226 offset:32
	ds_read_u16 v22, v226 offset:48
	ds_read_u16 v26, v226 offset:64
	ds_read_u16 v30, v226 offset:80
	ds_read_u16 v34, v226 offset:96
	ds_read_u16 v38, v226 offset:112
	ds_read_u16 v42, v226 offset:128
	ds_read_u16 v50, v226 offset:272
	ds_read_u16 v114, v226 offset:416
	ds_read_u16 v58, v226 offset:288
	ds_read_u16 v118, v226 offset:432
	s_waitcnt lgkmcnt(4)
	v_mad_u32_u24 v42, v42, s50, v203
	s_waitcnt lgkmcnt(3)
	v_mad_u32_u24 v50, v50, s50, v203
	global_load_dwordx4 v[46:49], v42, s[6:7] offset:2048
	s_waitcnt lgkmcnt(1)
	v_mad_u32_u24 v58, v58, s50, v203
	global_load_dwordx4 v[50:53], v50, s[6:7] offset:2048
	ds_read_u16 v42, v226 offset:144
	global_load_dwordx4 v[58:61], v58, s[6:7] offset:2048
	ds_read_u16 v66, v226 offset:304
	ds_read_u16 v122, v226 offset:448
	ds_read_u16 v74, v226 offset:320
	ds_read_u16 v128, v226 offset:464
	s_waitcnt lgkmcnt(4)
	v_mad_u32_u24 v42, v42, s50, v203
	global_load_dwordx4 v[54:57], v42, s[6:7] offset:2048
	ds_read_u16 v42, v226 offset:160
	s_waitcnt lgkmcnt(4)
	v_mad_u32_u24 v66, v66, s50, v203
	global_load_dwordx4 v[66:69], v66, s[6:7] offset:2048
	s_waitcnt lgkmcnt(2)
	v_mad_u32_u24 v74, v74, s50, v203
	global_load_dwordx4 v[74:77], v74, s[6:7] offset:2048
	s_waitcnt lgkmcnt(0)
	v_mad_u32_u24 v42, v42, s50, v203
	global_load_dwordx4 v[62:65], v42, s[6:7] offset:2048
	ds_read_u16 v42, v226 offset:176
	ds_read_u16 v82, v226 offset:336
	ds_read_u16 v132, v226 offset:480
	ds_read_u16 v90, v226 offset:352
	ds_read_u16 v136, v226 offset:496
	s_waitcnt lgkmcnt(4)
	v_mad_u32_u24 v42, v42, s50, v203
	global_load_dwordx4 v[70:73], v42, s[6:7] offset:2048
	ds_read_u16 v42, v226 offset:192
	s_waitcnt lgkmcnt(4)
	v_mad_u32_u24 v82, v82, s50, v203
	global_load_dwordx4 v[82:85], v82, s[6:7] offset:2048
	v_mad_u32_u24 v10, v10, s50, v203
	global_load_dwordx4 v[10:13], v10, s[6:7] offset:2048
	s_waitcnt lgkmcnt(0)
	v_mad_u32_u24 v42, v42, s50, v203
	global_load_dwordx4 v[78:81], v42, s[6:7] offset:2048
	ds_read_u16 v42, v226 offset:208
	v_mad_u32_u24 v14, v14, s50, v203
	global_load_dwordx4 v[14:17], v14, s[6:7] offset:2048
	v_mad_u32_u24 v18, v18, s50, v203
	global_load_dwordx4 v[18:21], v18, s[6:7] offset:2048
	v_mad_u32_u24 v22, v22, s50, v203
	s_waitcnt lgkmcnt(0)
	v_mad_u32_u24 v42, v42, s50, v203
	v_mad_u32_u24 v90, v90, s50, v203
	global_load_dwordx4 v[22:25], v22, s[6:7] offset:2048
	v_mad_u32_u24 v26, v26, s50, v203
	global_load_dwordx4 v[86:89], v42, s[6:7] offset:2048
	ds_read_u16 v98, v226 offset:368
	global_load_dwordx4 v[90:93], v90, s[6:7] offset:2048
	ds_read_u16 v42, v226 offset:224
	global_load_dwordx4 v[26:29], v26, s[6:7] offset:2048
	v_mad_u32_u24 v30, v30, s50, v203
	global_load_dwordx4 v[30:33], v30, s[6:7] offset:2048
	v_mad_u32_u24 v34, v34, s50, v203
	global_load_dwordx4 v[34:37], v34, s[6:7] offset:2048
	v_mad_u32_u24 v38, v38, s50, v203
	global_load_dwordx4 v[38:41], v38, s[6:7] offset:2048
	s_waitcnt lgkmcnt(0)
	v_mad_u32_u24 v42, v42, s50, v203
	v_mad_u32_u24 v98, v98, s50, v203
	global_load_dwordx4 v[94:97], v42, s[6:7] offset:2048
	ds_read_u16 v102, v226 offset:384
	global_load_dwordx4 v[98:101], v98, s[6:7] offset:2048
	ds_read_u16 v42, v226 offset:240
	ds_read_u16 v110, v226 offset:400
	v_lshlrev_b32_e32 v140, 7, v127
	s_waitcnt lgkmcnt(2)
	v_mad_u32_u24 v102, v102, s50, v203
	global_load_dwordx4 v[102:105], v102, s[6:7] offset:2048
	s_waitcnt lgkmcnt(1)
	v_mad_u32_u24 v42, v42, s50, v203
	global_load_dwordx4 v[106:109], v42, s[6:7] offset:2048
	ds_read_u16 v42, v226 offset:256
	v_bitop3_b32 v127, v127, v220, 7 bitop3:0x78
	s_waitcnt lgkmcnt(1)
	v_mad_u32_u24 v110, v110, s50, v203
	v_lshl_add_u32 v225, v126, 14, v214
	v_lshlrev_b32_e32 v127, 4, v127
	s_waitcnt lgkmcnt(0)
	v_mad_u32_u24 v42, v42, s50, v203
	global_load_dwordx4 v[42:45], v42, s[6:7] offset:2048
	v_mad_u32_u24 v114, v114, s50, v203
	global_load_dwordx4 v[110:113], v110, s[6:7] offset:2048
	v_mad_u32_u24 v118, v118, s50, v203
	v_mad_u32_u24 v122, v122, s50, v203
	v_mad_u32_u24 v128, v128, s50, v203
	v_mad_u32_u24 v132, v132, s50, v203
	v_mad_u32_u24 v136, v136, s50, v203
	v_add3_u32 v127, v225, v127, v140
	global_load_dwordx4 v[114:117], v114, s[6:7] offset:2048
	v_and_b32_e32 v126, 7, v220
	global_load_dwordx4 v[118:121], v118, s[6:7] offset:2048
	v_lshlrev_b32_e32 v228, 2, v227
	global_load_dwordx4 v[122:125], v122, s[6:7] offset:2048
	v_cmp_eq_u32_e32 vcc, 0, v219
	global_load_dwordx4 v[128:131], v128, s[6:7] offset:2048
	s_nop 0
	global_load_dwordx4 v[132:135], v132, s[6:7] offset:2048
	s_nop 0
	global_load_dwordx4 v[136:139], v136, s[6:7] offset:2048
	s_waitcnt lgkmcnt(0)
	s_waitcnt vmcnt(22)
	ds_write_b128 v127, v[10:13]
	s_waitcnt vmcnt(20)
	ds_write_b128 v127, v[14:17] offset:1024
	s_waitcnt vmcnt(19)
	ds_write_b128 v127, v[18:21] offset:2048
	s_waitcnt vmcnt(18)
	ds_write_b128 v127, v[22:25] offset:3072
	s_waitcnt vmcnt(15)
	ds_write_b128 v127, v[26:29] offset:4096
	s_waitcnt vmcnt(14)
	ds_write_b128 v127, v[30:33] offset:5120
	s_waitcnt vmcnt(13)
	ds_write_b128 v127, v[34:37] offset:6144
	s_waitcnt vmcnt(12)
	ds_write_b128 v127, v[38:41] offset:7168
	ds_write_b128 v127, v[46:49] offset:8192
	ds_write_b128 v127, v[54:57] offset:9216
	ds_write_b128 v127, v[62:65] offset:10240
	ds_write_b128 v127, v[70:73] offset:11264
	ds_write_b128 v127, v[78:81] offset:12288
	ds_write_b128 v127, v[86:89] offset:13312
	s_waitcnt vmcnt(11)
; #define LOADKV(BASECOL, SH) { _Pragma("unroll") for (int rr = 0; rr < 16; ++rr) { \
;       const unsigned vo_ = (unsigned)mySel[(SH) * 128 + rr * 8 + (lane >> 3)] * 4608u + (unsigned)(hkv * 128 + (lane & 7) * 16); \
;       vreg[rr] = *(const bf16x8*)((const char*)(Pb + (BASECOL)) + (size_t)vo_); } }
; #define LOADV(SH) LOADKV(1280, SH)
; #define KWRITE() { _Pragma("unroll") for (int rr = 0; rr < 16; ++rr) { const int row_ = rr * 8 + (lane >> 3), piece_ = lane & 7; \
;       *(bf16x8*)(Ks + row_ * 128 + ((piece_ ^ (row_ & 7)) * 16)) = vreg[rr]; } }
; #define LOADKV2(BASECOL, SH) { _Pragma("unroll") for (int rr = 0; rr < 16; ++rr) { \
;       const unsigned vo_ = (unsigned)mySel[(SH) * 128 + rr * 8 + (lane >> 3)] * 4608u + (unsigned)(hkv * 128 + (lane & 7) * 16); \
;       vreg2[rr] = *(const bf16x8*)((const char*)(Pb + (BASECOL)) + (size_t)vo_); } }
; #define KWRITE2() { _Pragma("unroll") for (int rr = 0; rr < 16; ++rr) { const int row_ = rr * 8 + (lane >> 3), piece_ = lane & 7; \
;       *(bf16x8*)(Ks + row_ * 128 + ((piece_ ^ (row_ & 7)) * 16)) = vreg2[rr]; } }
; DI void phase_mix_b2(int wv_, int vb_, int nvb_, char* ws_, const Ctx& p, char* smem) {
;     ...
;     bf16x8 vreg2[16];
;     ...
;     LOADKV(1024, 0)
;     LOADKV2(1024, 1)
;     asm volatile("s_waitcnt lgkmcnt(0)" ::: "memory");
;     KWRITE()
;     asm volatile("s_waitcnt lgkmcnt(0)" ::: "memory");
;     QKSTAGE(0)
;     asm volatile("s_waitcnt lgkmcnt(0)" ::: "memory");
;     KWRITE2()
;     LOADV(0)
;     asm volatile("s_waitcnt lgkmcnt(0)" ::: "memory");
;     QKSTAGE(1)
;     asm volatile("s_waitcnt lgkmcnt(0)" ::: "memory");
;     LOADKV2(1280, 1)
	ds_write_b128 v127, v[94:97] offset:14336
	s_waitcnt vmcnt(8)
	ds_write_b128 v127, v[106:109] offset:15360
	v_bitop3_b32 v10, v219, v220, 7 bitop3:0x78
	v_lshl_add_u32 v16, v0, 7, v225
	s_waitcnt lgkmcnt(0)
	v_lshl_add_u32 v10, v10, 4, v16
	ds_read_b128 v[12:15], v10
	v_bitop3_b32 v11, v219, v126, 4 bitop3:0x36
	v_lshl_add_u32 v11, v11, 4, v16
	ds_read_b128 v[16:19], v11
	s_waitcnt lgkmcnt(1)
	v_mfma_f32_16x16x32_bf16 v[12:15], v[12:15], v[2:5], 0
	s_waitcnt lgkmcnt(0)
	v_mfma_f32_16x16x32_bf16 v[190:193], v[16:19], v[6:9], v[12:15]
	s_nop 5
	ds_read_b128 v[12:15], v10 offset:2048
	ds_read_b128 v[16:19], v11 offset:2048
	s_waitcnt lgkmcnt(1)
	v_mfma_f32_16x16x32_bf16 v[12:15], v[12:15], v[2:5], 0
	s_waitcnt lgkmcnt(0)
	v_mfma_f32_16x16x32_bf16 v[186:189], v[16:19], v[6:9], v[12:15]
	s_nop 5
	ds_read_b128 v[12:15], v10 offset:4096
	ds_read_b128 v[16:19], v11 offset:4096
	s_waitcnt lgkmcnt(1)
	v_mfma_f32_16x16x32_bf16 v[12:15], v[12:15], v[2:5], 0
	s_waitcnt lgkmcnt(0)
	v_mfma_f32_16x16x32_bf16 v[182:185], v[16:19], v[6:9], v[12:15]
	s_nop 5
	ds_read_b128 v[12:15], v10 offset:6144
	ds_read_b128 v[16:19], v11 offset:6144
	s_waitcnt lgkmcnt(1)
	v_mfma_f32_16x16x32_bf16 v[12:15], v[12:15], v[2:5], 0
	s_waitcnt lgkmcnt(0)
	v_mfma_f32_16x16x32_bf16 v[178:181], v[16:19], v[6:9], v[12:15]
	s_nop 5
	ds_read_b128 v[12:15], v10 offset:8192
	ds_read_b128 v[16:19], v11 offset:8192
	s_waitcnt lgkmcnt(1)
	v_mfma_f32_16x16x32_bf16 v[12:15], v[12:15], v[2:5], 0
	s_waitcnt lgkmcnt(0)
	v_mfma_f32_16x16x32_bf16 v[174:177], v[16:19], v[6:9], v[12:15]
	s_nop 5
	ds_read_b128 v[12:15], v10 offset:10240
	ds_read_b128 v[16:19], v11 offset:10240
	s_waitcnt lgkmcnt(1)
	v_mfma_f32_16x16x32_bf16 v[12:15], v[12:15], v[2:5], 0
	s_waitcnt lgkmcnt(0)
	v_mfma_f32_16x16x32_bf16 v[166:169], v[16:19], v[6:9], v[12:15]
	s_nop 5
	ds_read_b128 v[12:15], v10 offset:12288
	ds_read_b128 v[16:19], v11 offset:12288
	s_waitcnt lgkmcnt(1)
	v_mfma_f32_16x16x32_bf16 v[12:15], v[12:15], v[2:5], 0
	s_waitcnt lgkmcnt(0)
	v_mfma_f32_16x16x32_bf16 v[158:161], v[16:19], v[6:9], v[12:15]
	s_nop 5
	ds_read_b128 v[12:15], v10 offset:14336
	ds_read_b128 v[16:19], v11 offset:14336
	s_waitcnt lgkmcnt(0)
	s_waitcnt vmcnt(7)
	ds_write_b128 v127, v[42:45]
	ds_write_b128 v127, v[50:53] offset:1024
	ds_write_b128 v127, v[58:61] offset:2048
	ds_write_b128 v127, v[66:69] offset:3072
	ds_write_b128 v127, v[74:77] offset:4096
	ds_write_b128 v127, v[82:85] offset:5120
	ds_write_b128 v127, v[90:93] offset:6144
	ds_write_b128 v127, v[98:101] offset:7168
	ds_write_b128 v127, v[102:105] offset:8192
	s_waitcnt vmcnt(6)
	ds_write_b128 v127, v[110:113] offset:9216
	s_waitcnt vmcnt(5)
	ds_write_b128 v127, v[114:117] offset:10240
	s_waitcnt vmcnt(4)
	ds_write_b128 v127, v[118:121] offset:11264
	s_waitcnt vmcnt(3)
	ds_write_b128 v127, v[122:125] offset:12288
	s_waitcnt vmcnt(2)
	ds_write_b128 v127, v[128:131] offset:13312
	s_waitcnt vmcnt(1)
	ds_write_b128 v127, v[132:135] offset:14336
	s_waitcnt vmcnt(0)
	ds_write_b128 v127, v[136:139] offset:15360
	s_waitcnt lgkmcnt(14)
	v_mfma_f32_16x16x32_bf16 v[12:15], v[12:15], v[2:5], 0
	v_mfma_f32_16x16x32_bf16 v[150:153], v[16:19], v[6:9], v[12:15]
	s_nop 6
	ds_read_u16 v12, v226
	ds_read_u16 v13, v226 offset:16
	ds_read_u16 v14, v226 offset:32
	ds_read_u16 v15, v226 offset:48
	s_waitcnt lgkmcnt(3)
	v_mad_u32_u24 v12, v12, s50, v203
	global_load_dwordx4 v[18:21], v12, s[6:7] offset:2560
	s_waitcnt lgkmcnt(2)
	v_mad_u32_u24 v12, v13, s50, v203
	global_load_dwordx4 v[22:25], v12, s[6:7] offset:2560
	s_waitcnt lgkmcnt(1)
	v_mad_u32_u24 v12, v14, s50, v203
	global_load_dwordx4 v[26:29], v12, s[6:7] offset:2560
	s_waitcnt lgkmcnt(0)
	v_mad_u32_u24 v12, v15, s50, v203
	global_load_dwordx4 v[30:33], v12, s[6:7] offset:2560
	ds_read_u16 v12, v226 offset:64
	s_waitcnt lgkmcnt(0)
	v_mad_u32_u24 v12, v12, s50, v203
	global_load_dwordx4 v[42:45], v12, s[6:7] offset:2560
	ds_read_u16 v12, v226 offset:80
	s_waitcnt lgkmcnt(0)
	v_mad_u32_u24 v12, v12, s50, v203
	global_load_dwordx4 v[50:53], v12, s[6:7] offset:2560
	ds_read_u16 v12, v226 offset:96
	s_waitcnt lgkmcnt(0)
	v_mad_u32_u24 v12, v12, s50, v203
	global_load_dwordx4 v[54:57], v12, s[6:7] offset:2560
	ds_read_u16 v12, v226 offset:112
	s_waitcnt lgkmcnt(0)
	v_mad_u32_u24 v12, v12, s50, v203
	global_load_dwordx4 v[62:65], v12, s[6:7] offset:2560
	ds_read_u16 v12, v226 offset:128
	s_waitcnt lgkmcnt(0)
	v_mad_u32_u24 v12, v12, s50, v203
	global_load_dwordx4 v[74:77], v12, s[6:7] offset:2560
	ds_read_u16 v12, v226 offset:144
	s_waitcnt lgkmcnt(0)
	v_mad_u32_u24 v12, v12, s50, v203
	global_load_dwordx4 v[82:85], v12, s[6:7] offset:2560
	ds_read_u16 v12, v226 offset:160
	s_waitcnt lgkmcnt(0)
	v_mad_u32_u24 v12, v12, s50, v203
	global_load_dwordx4 v[90:93], v12, s[6:7] offset:2560
	ds_read_u16 v12, v226 offset:176
	s_waitcnt lgkmcnt(0)
	v_mad_u32_u24 v12, v12, s50, v203
	global_load_dwordx4 v[98:101], v12, s[6:7] offset:2560
	ds_read_u16 v12, v226 offset:192
	s_waitcnt lgkmcnt(0)
	v_mad_u32_u24 v12, v12, s50, v203
	global_load_dwordx4 v[106:109], v12, s[6:7] offset:2560
	ds_read_u16 v12, v226 offset:208
	s_waitcnt lgkmcnt(0)
	v_mad_u32_u24 v12, v12, s50, v203
	global_load_dwordx4 v[114:117], v12, s[6:7] offset:2560
	ds_read_u16 v12, v226 offset:224
	s_waitcnt lgkmcnt(0)
	v_mad_u32_u24 v12, v12, s50, v203
	global_load_dwordx4 v[122:125], v12, s[6:7] offset:2560
	ds_read_u16 v12, v226 offset:240
	s_waitcnt lgkmcnt(0)
	v_mad_u32_u24 v12, v12, s50, v203
	global_load_dwordx4 v[126:129], v12, s[6:7] offset:2560
	s_waitcnt lgkmcnt(0)
	ds_read_b128 v[12:15], v10
	ds_read_b128 v[34:37], v11
	s_waitcnt lgkmcnt(1)
; #define LOADKV(BASECOL, SH) { _Pragma("unroll") for (int rr = 0; rr < 16; ++rr) { \
;       const unsigned vo_ = (unsigned)mySel[(SH) * 128 + rr * 8 + (lane >> 3)] * 4608u + (unsigned)(hkv * 128 + (lane & 7) * 16); \
;       vreg[rr] = *(const bf16x8*)((const char*)(Pb + (BASECOL)) + (size_t)vo_); } }
; #define LOADV(SH) LOADKV(1280, SH)
; #define KWRITE() { _Pragma("unroll") for (int rr = 0; rr < 16; ++rr) { const int row_ = rr * 8 + (lane >> 3), piece_ = lane & 7; \
;       *(bf16x8*)(Ks + row_ * 128 + ((piece_ ^ (row_ & 7)) * 16)) = vreg[rr]; } }
; #define LOADKV2(BASECOL, SH) { _Pragma("unroll") for (int rr = 0; rr < 16; ++rr) { \
;       const unsigned vo_ = (unsigned)mySel[(SH) * 128 + rr * 8 + (lane >> 3)] * 4608u + (unsigned)(hkv * 128 + (lane & 7) * 16); \
;       vreg2[rr] = *(const bf16x8*)((const char*)(Pb + (BASECOL)) + (size_t)vo_); } }
; #define KWRITE2() { _Pragma("unroll") for (int rr = 0; rr < 16; ++rr) { const int row_ = rr * 8 + (lane >> 3), piece_ = lane & 7; \
;       *(bf16x8*)(Ks + row_ * 128 + ((piece_ ^ (row_ & 7)) * 16)) = vreg2[rr]; } }
; DI void phase_mix_b2(int wv_, int vb_, int nvb_, char* ws_, const Ctx& p, char* smem) {
;     ...
;     bf16x8 vreg2[16];
;     ...
;     LOADKV(1024, 0)
;     LOADKV2(1024, 1)
;     asm volatile("s_waitcnt lgkmcnt(0)" ::: "memory");
;     KWRITE()
;     asm volatile("s_waitcnt lgkmcnt(0)" ::: "memory");
;     QKSTAGE(0)
;     asm volatile("s_waitcnt lgkmcnt(0)" ::: "memory");
;     KWRITE2()
;     LOADV(0)
;     asm volatile("s_waitcnt lgkmcnt(0)" ::: "memory");
;     QKSTAGE(1)
;     asm volatile("s_waitcnt lgkmcnt(0)" ::: "memory");
;     LOADKV2(1280, 1)
;     ...
;     float mx = -INFINITY;
; #pragma unroll
;     for (int kb = 0; kb < 16; ++kb)
; #pragma unroll
;       for (int i = 0; i < 4; ++i) {
;         const unsigned bk4 = *(const unsigned*)(mySelb + kb * 16 + fq * 4);
;         const int bk = (bk4 >> (8 * i)) & 255;
;         const float bv = sbias[bk * 16 + hkv * 4 + (n16 & 3)];
;         const float v = lg[kb][i] + bv;
;         lg[kb][i] = v; mx = fmaxf(mx, v);
;       }
	v_mfma_f32_16x16x32_bf16 v[12:15], v[12:15], v[2:5], 0
	s_waitcnt lgkmcnt(0)
	v_mfma_f32_16x16x32_bf16 v[170:173], v[34:37], v[6:9], v[12:15]
	s_nop 5
	ds_read_b128 v[12:15], v10 offset:2048
	ds_read_b128 v[34:37], v11 offset:2048
	s_waitcnt lgkmcnt(1)
	v_mfma_f32_16x16x32_bf16 v[12:15], v[12:15], v[2:5], 0
	s_waitcnt lgkmcnt(0)
	v_mfma_f32_16x16x32_bf16 v[162:165], v[34:37], v[6:9], v[12:15]
	s_nop 5
	ds_read_b128 v[12:15], v10 offset:4096
	ds_read_b128 v[34:37], v11 offset:4096
	s_waitcnt lgkmcnt(1)
	v_mfma_f32_16x16x32_bf16 v[12:15], v[12:15], v[2:5], 0
	s_waitcnt lgkmcnt(0)
	v_mfma_f32_16x16x32_bf16 v[154:157], v[34:37], v[6:9], v[12:15]
	s_nop 5
	ds_read_b128 v[12:15], v10 offset:6144
	ds_read_b128 v[34:37], v11 offset:6144
	s_waitcnt lgkmcnt(1)
	v_mfma_f32_16x16x32_bf16 v[12:15], v[12:15], v[2:5], 0
	s_waitcnt lgkmcnt(0)
	v_mfma_f32_16x16x32_bf16 v[146:149], v[34:37], v[6:9], v[12:15]
	s_nop 5
	ds_read_b128 v[12:15], v10 offset:8192
	ds_read_b128 v[34:37], v11 offset:8192
	s_waitcnt lgkmcnt(1)
	v_mfma_f32_16x16x32_bf16 v[12:15], v[12:15], v[2:5], 0
	s_waitcnt lgkmcnt(0)
	v_mfma_f32_16x16x32_bf16 v[142:145], v[34:37], v[6:9], v[12:15]
	s_nop 5
	ds_read_b128 v[12:15], v10 offset:10240
	ds_read_b128 v[34:37], v11 offset:10240
	s_waitcnt lgkmcnt(1)
	v_mfma_f32_16x16x32_bf16 v[12:15], v[12:15], v[2:5], 0
	s_waitcnt lgkmcnt(0)
	v_mfma_f32_16x16x32_bf16 v[138:141], v[34:37], v[6:9], v[12:15]
	s_nop 5
	ds_read_b128 v[12:15], v10 offset:12288
	ds_read_b128 v[34:37], v11 offset:12288
	s_waitcnt lgkmcnt(1)
	v_mfma_f32_16x16x32_bf16 v[12:15], v[12:15], v[2:5], 0
	s_waitcnt lgkmcnt(0)
	v_mfma_f32_16x16x32_bf16 v[134:137], v[34:37], v[6:9], v[12:15]
	s_nop 5
	ds_read_b128 v[12:15], v10 offset:14336
	ds_read_b128 v[34:37], v11 offset:14336
	s_waitcnt lgkmcnt(0)
	s_waitcnt lgkmcnt(1)
	v_mfma_f32_16x16x32_bf16 v[2:5], v[12:15], v[2:5], 0
	s_waitcnt lgkmcnt(0)
	v_mfma_f32_16x16x32_bf16 v[130:133], v[34:37], v[6:9], v[2:5]
	s_nop 5
	ds_read_u16 v2, v226 offset:256
	ds_read_u16 v6, v226 offset:272
	ds_read_u16 v10, v226 offset:288
	ds_read_u16 v14, v226 offset:304
	ds_read_u16 v34, v226 offset:320
	ds_read_u16 v38, v226 offset:336
	ds_read_u16 v46, v226 offset:352
	ds_read_u16 v58, v226 offset:368
	ds_read_u16 v66, v226 offset:384
	ds_read_u16 v70, v226 offset:400
	ds_read_u16 v78, v226 offset:416
	ds_read_u16 v86, v226 offset:432
	ds_read_u16 v94, v226 offset:448
	ds_read_u16 v102, v226 offset:464
	ds_read_u16 v110, v226 offset:480
	ds_read_u16 v118, v226 offset:496
	v_lshlrev_b32_e32 v226, 2, v219
	s_waitcnt lgkmcnt(14)
	v_mad_u32_u24 v2, v2, s50, v203
	v_mad_u32_u24 v6, v6, s50, v203
	s_waitcnt lgkmcnt(13)
	v_mad_u32_u24 v10, v10, s50, v203
	s_waitcnt lgkmcnt(12)
	v_mad_u32_u24 v14, v14, s50, v203
	s_waitcnt lgkmcnt(11)
	v_mad_u32_u24 v34, v34, s50, v203
	s_waitcnt lgkmcnt(10)
	v_mad_u32_u24 v38, v38, s50, v203
	s_waitcnt lgkmcnt(9)
	v_mad_u32_u24 v46, v46, s50, v203
	s_waitcnt lgkmcnt(8)
	v_mad_u32_u24 v58, v58, s50, v203
	s_waitcnt lgkmcnt(7)
	v_mad_u32_u24 v66, v66, s50, v203
	s_waitcnt lgkmcnt(6)
	v_mad_u32_u24 v70, v70, s50, v203
	s_waitcnt lgkmcnt(5)
	v_mad_u32_u24 v78, v78, s50, v203
	s_waitcnt lgkmcnt(4)
	v_mad_u32_u24 v86, v86, s50, v203
	s_waitcnt lgkmcnt(3)
	v_mad_u32_u24 v94, v94, s50, v203
	s_waitcnt lgkmcnt(2)
	v_mad_u32_u24 v102, v102, s50, v203
	s_waitcnt lgkmcnt(1)
	v_mad_u32_u24 v110, v110, s50, v203
	s_waitcnt lgkmcnt(0)
	v_mad_u32_u24 v118, v118, s50, v203
	v_add_u32_e32 v229, v202, v226
	global_load_dwordx4 v[2:5], v2, s[6:7] offset:2560
	s_nop 0
	global_load_dwordx4 v[6:9], v6, s[6:7] offset:2560
	s_nop 0
	global_load_dwordx4 v[10:13], v10, s[6:7] offset:2560
	s_nop 0
	global_load_dwordx4 v[14:17], v14, s[6:7] offset:2560
	s_nop 0
	global_load_dwordx4 v[34:37], v34, s[6:7] offset:2560
	s_nop 0
	global_load_dwordx4 v[38:41], v38, s[6:7] offset:2560
	s_nop 0
	global_load_dwordx4 v[46:49], v46, s[6:7] offset:2560
	s_nop 0
	global_load_dwordx4 v[58:61], v58, s[6:7] offset:2560
	s_nop 0
	global_load_dwordx4 v[66:69], v66, s[6:7] offset:2560
	s_nop 0
	global_load_dwordx4 v[70:73], v70, s[6:7] offset:2560
	s_nop 0
	global_load_dwordx4 v[78:81], v78, s[6:7] offset:2560
	s_nop 0
	global_load_dwordx4 v[86:89], v86, s[6:7] offset:2560
	s_nop 0
	global_load_dwordx4 v[94:97], v94, s[6:7] offset:2560
	s_nop 0
	global_load_dwordx4 v[102:105], v102, s[6:7] offset:2560
	s_nop 0
	global_load_dwordx4 v[110:113], v110, s[6:7] offset:2560
	s_nop 0
	global_load_dwordx4 v[118:121], v118, s[6:7] offset:2560
	s_movk_i32 s6, 0x60
	v_add_u32_e32 v203, v216, v228
	ds_read2_b32 v[194:195], v229 offset1:4
	ds_read2_b32 v[196:197], v229 offset0:8 offset1:12
	ds_read2_b32 v[198:199], v229 offset0:16 offset1:20
	ds_read2_b32 v[230:231], v229 offset0:24 offset1:28
	s_waitcnt lgkmcnt(3)
	v_bfe_u32 v232, v194, 0, 8
	v_lshl_add_u32 v232, v232, 6, v203
	ds_read_b32 v232, v232
	v_bfe_u32 v233, v194, 16, 8
	v_lshl_add_u32 v233, v233, 6, v203
	ds_read_b32 v233, v233
	v_bfe_u32 v234, v194, 8, 8
	v_lshl_add_u32 v234, v234, 6, v203
	ds_read_b32 v234, v234
	v_bfe_u32 v235, v194, 24, 8
	v_lshl_add_u32 v235, v235, 6, v203
	ds_read_b32 v235, v235
	v_bfe_u32 v236, v195, 0, 8
	v_lshl_add_u32 v236, v236, 6, v203
	ds_read_b32 v236, v236
	v_bfe_u32 v237, v195, 8, 8
	v_lshl_add_u32 v237, v237, 6, v203
	ds_read_b32 v237, v237
	v_bfe_u32 v238, v195, 16, 8
	v_lshl_add_u32 v238, v238, 6, v203
	ds_read_b32 v238, v238
	v_bfe_u32 v239, v195, 24, 8
	v_lshl_add_u32 v239, v239, 6, v203
	ds_read_b32 v239, v239
	s_waitcnt lgkmcnt(10)
; DI void phase_mix_b2(int wv_, int vb_, int nvb_, char* ws_, const Ctx& p, char* smem) {
;     ...
;     float mx = -INFINITY;
; #pragma unroll
;     for (int kb = 0; kb < 16; ++kb)
; #pragma unroll
;       for (int i = 0; i < 4; ++i) {
;         const unsigned bk4 = *(const unsigned*)(mySelb + kb * 16 + fq * 4);
;         const int bk = (bk4 >> (8 * i)) & 255;
;         const float bv = sbias[bk * 16 + hkv * 4 + (n16 & 3)];
;         const float v = lg[kb][i] + bv;
;         lg[kb][i] = v; mx = fmaxf(mx, v);
;       }
	v_bfe_u32 v240, v196, 0, 8
	v_lshl_add_u32 v240, v240, 6, v203
	ds_read_b32 v240, v240
	v_bfe_u32 v241, v196, 8, 8
	v_lshl_add_u32 v241, v241, 6, v203
	ds_read_b32 v241, v241
	v_bfe_u32 v246, v196, 16, 8
	v_lshl_add_u32 v246, v246, 6, v203
	ds_read_b32 v246, v246
	v_bfe_u32 v247, v196, 24, 8
	v_lshl_add_u32 v247, v247, 6, v203
	ds_read_b32 v247, v247
	v_bfe_u32 v248, v197, 0, 8
	v_lshl_add_u32 v248, v248, 6, v203
	ds_read_b32 v248, v248
	v_bfe_u32 v249, v197, 8, 8
	v_lshl_add_u32 v249, v249, 6, v203
	ds_read_b32 v249, v249
	v_bfe_u32 v250, v197, 16, 8
	v_lshl_add_u32 v250, v250, 6, v203
	ds_read_b32 v250, v250
	v_bfe_u32 v251, v197, 24, 8
	v_lshl_add_u32 v251, v251, 6, v203
	ds_read_b32 v251, v251
	s_waitcnt lgkmcnt(8)
	v_add_f32_e32 v190, v190, v232
	v_add_f32_e32 v192, v192, v233
	v_add_f32_e32 v191, v191, v234
	v_add_f32_e32 v193, v193, v235
	v_add_f32_e32 v227, v186, v236
	v_add_f32_e32 v186, v187, v237
	v_add_f32_e32 v187, v188, v238
	v_add_f32_e32 v188, v189, v239
	v_max3_f32 v209, v190, s39, v192
	v_max3_f32 v209, v209, v191, v193
	v_max3_f32 v209, v209, v227, v186
	v_max3_f32 v209, v209, v187, v188
	v_bfe_u32 v232, v198, 0, 8
	v_lshl_add_u32 v232, v232, 6, v203
	ds_read_b32 v232, v232
	v_bfe_u32 v233, v198, 8, 8
	v_lshl_add_u32 v233, v233, 6, v203
	ds_read_b32 v233, v233
	v_bfe_u32 v234, v198, 16, 8
	v_lshl_add_u32 v234, v234, 6, v203
	ds_read_b32 v234, v234
	v_bfe_u32 v235, v198, 24, 8
	v_lshl_add_u32 v235, v235, 6, v203
	ds_read_b32 v235, v235
	v_bfe_u32 v236, v199, 0, 8
	v_lshl_add_u32 v236, v236, 6, v203
	ds_read_b32 v236, v236
	v_bfe_u32 v237, v199, 8, 8
	v_lshl_add_u32 v237, v237, 6, v203
	ds_read_b32 v237, v237
	v_bfe_u32 v238, v199, 16, 8
	v_lshl_add_u32 v238, v238, 6, v203
	ds_read_b32 v238, v238
	v_bfe_u32 v239, v199, 24, 8
	v_lshl_add_u32 v239, v239, 6, v203
	ds_read_b32 v239, v239
	s_waitcnt lgkmcnt(8)
	v_add_f32_e32 v189, v182, v240
	v_add_f32_e32 v182, v183, v241
	v_add_f32_e32 v183, v184, v246
	v_add_f32_e32 v184, v185, v247
	v_add_f32_e32 v185, v178, v248
	v_add_f32_e32 v178, v179, v249
	v_add_f32_e32 v179, v180, v250
	v_add_f32_e32 v180, v181, v251
	v_max3_f32 v209, v209, v189, v182
	v_max3_f32 v209, v209, v183, v184
	v_max3_f32 v209, v209, v185, v178
	v_max3_f32 v209, v209, v179, v180
	v_bfe_u32 v240, v230, 0, 8
	v_lshl_add_u32 v240, v240, 6, v203
	ds_read_b32 v240, v240
	v_bfe_u32 v241, v230, 8, 8
	v_lshl_add_u32 v241, v241, 6, v203
	ds_read_b32 v241, v241
	v_bfe_u32 v246, v230, 16, 8
	v_lshl_add_u32 v246, v246, 6, v203
	ds_read_b32 v246, v246
	v_bfe_u32 v247, v230, 24, 8
	v_lshl_add_u32 v247, v247, 6, v203
	ds_read_b32 v247, v247
	v_bfe_u32 v248, v231, 0, 8
	v_lshl_add_u32 v248, v248, 6, v203
	ds_read_b32 v248, v248
	v_bfe_u32 v249, v231, 8, 8
	v_lshl_add_u32 v249, v249, 6, v203
	ds_read_b32 v249, v249
	v_bfe_u32 v250, v231, 16, 8
	v_lshl_add_u32 v250, v250, 6, v203
	ds_read_b32 v250, v250
	v_bfe_u32 v251, v231, 24, 8
	v_lshl_add_u32 v251, v251, 6, v203
	ds_read_b32 v251, v251
	s_waitcnt lgkmcnt(8)
	v_add_f32_e32 v181, v174, v232
	v_add_f32_e32 v174, v175, v233
	v_add_f32_e32 v175, v176, v234
	v_add_f32_e32 v176, v177, v235
	v_add_f32_e32 v177, v166, v236
	v_add_f32_e32 v166, v167, v237
	v_add_f32_e32 v167, v168, v238
	v_add_f32_e32 v168, v169, v239
	v_max3_f32 v209, v209, v181, v174
	v_max3_f32 v209, v209, v175, v176
	v_max3_f32 v209, v209, v177, v166
	v_max3_f32 v209, v209, v167, v168
	s_waitcnt lgkmcnt(0)
	v_add_f32_e32 v169, v158, v240
	v_add_f32_e32 v158, v159, v241
	v_add_f32_e32 v159, v160, v246
	v_add_f32_e32 v160, v161, v247
	v_add_f32_e32 v161, v150, v248
	v_add_f32_e32 v150, v151, v249
	v_add_f32_e32 v151, v152, v250
	v_add_f32_e32 v152, v153, v251
	v_max3_f32 v209, v209, v169, v158
	v_max3_f32 v209, v209, v159, v160
	v_max3_f32 v209, v209, v161, v150
	v_max3_f32 v209, v209, v151, v152
	ds_read2_b32 v[194:195], v229 offset0:32 offset1:36
	ds_read2_b32 v[196:197], v229 offset0:40 offset1:44
	ds_read2_b32 v[198:199], v229 offset0:48 offset1:52
	ds_read2_b32 v[230:231], v229 offset0:56 offset1:60
	s_waitcnt lgkmcnt(3)
	v_bfe_u32 v232, v194, 0, 8
	v_lshl_add_u32 v232, v232, 6, v203
	ds_read_b32 v232, v232
	v_bfe_u32 v233, v194, 8, 8
	v_lshl_add_u32 v233, v233, 6, v203
	ds_read_b32 v233, v233
	v_bfe_u32 v234, v194, 16, 8
	v_lshl_add_u32 v234, v234, 6, v203
	ds_read_b32 v234, v234
	v_bfe_u32 v235, v194, 24, 8
	v_lshl_add_u32 v235, v235, 6, v203
	ds_read_b32 v235, v235
	v_bfe_u32 v236, v195, 0, 8
	v_lshl_add_u32 v236, v236, 6, v203
	ds_read_b32 v236, v236
	v_bfe_u32 v237, v195, 8, 8
	v_lshl_add_u32 v237, v237, 6, v203
	ds_read_b32 v237, v237
	v_bfe_u32 v238, v195, 16, 8
	v_lshl_add_u32 v238, v238, 6, v203
	ds_read_b32 v238, v238
	v_bfe_u32 v239, v195, 24, 8
	v_lshl_add_u32 v239, v239, 6, v203
	ds_read_b32 v239, v239
	s_waitcnt lgkmcnt(10)
	v_bfe_u32 v240, v196, 0, 8
	v_lshl_add_u32 v240, v240, 6, v203
	ds_read_b32 v240, v240
	v_bfe_u32 v241, v196, 8, 8
	v_lshl_add_u32 v241, v241, 6, v203
	ds_read_b32 v241, v241
	v_bfe_u32 v246, v196, 16, 8
	v_lshl_add_u32 v246, v246, 6, v203
	ds_read_b32 v246, v246
	v_bfe_u32 v247, v196, 24, 8
	v_lshl_add_u32 v247, v247, 6, v203
	ds_read_b32 v247, v247
	v_bfe_u32 v248, v197, 0, 8
	v_lshl_add_u32 v248, v248, 6, v203
	ds_read_b32 v248, v248
	v_bfe_u32 v249, v197, 8, 8
	v_lshl_add_u32 v249, v249, 6, v203
	ds_read_b32 v249, v249
	v_bfe_u32 v250, v197, 16, 8
	v_lshl_add_u32 v250, v250, 6, v203
	ds_read_b32 v250, v250
	v_bfe_u32 v251, v197, 24, 8
	v_lshl_add_u32 v251, v251, 6, v203
	ds_read_b32 v251, v251
	s_waitcnt lgkmcnt(8)
; DI float shx(float v, int m) { return __int_as_float(__builtin_amdgcn_ds_bpermute((lane_now() ^ m) << 2, __float_as_int(v))); }
; DI int shx(int v, int m) { return __builtin_amdgcn_ds_bpermute((lane_now() ^ m) << 2, v); }
; DI void phase_mix_b2(int wv_, int vb_, int nvb_, char* ws_, const Ctx& p, char* smem) {
;     ...
;     float mx = -INFINITY;
; #pragma unroll
;     for (int kb = 0; kb < 16; ++kb)
; #pragma unroll
;       for (int i = 0; i < 4; ++i) {
;         const unsigned bk4 = *(const unsigned*)(mySelb + kb * 16 + fq * 4);
;         const int bk = (bk4 >> (8 * i)) & 255;
;         const float bv = sbias[bk * 16 + hkv * 4 + (n16 & 3)];
;         const float v = lg[kb][i] + bv;
;         lg[kb][i] = v; mx = fmaxf(mx, v);
;       }
;     mx = fmaxf(mx, shx(mx, 16)); mx = fmaxf(mx, shx(mx, 32));
;     float sum = 0.f;
; #pragma unroll
;     for (int kb = 0; kb < 16; ++kb)
; #pragma unroll
;       for (int i = 0; i < 4; ++i) { float pv = __builtin_amdgcn_exp2f(lg[kb][i] - mx); lg[kb][i] = pv; sum += pv; }
;     sum += shx(sum, 16); sum += shx(sum, 32);
	v_add_f32_e32 v170, v170, v232
	v_add_f32_e32 v153, v171, v233
	v_add_f32_e32 v171, v172, v234
	v_add_f32_e32 v172, v173, v235
	v_add_f32_e32 v173, v162, v236
	v_add_f32_e32 v162, v163, v237
	v_add_f32_e32 v163, v164, v238
	v_add_f32_e32 v164, v165, v239
	v_max3_f32 v209, v209, v170, v153
	v_max3_f32 v209, v209, v171, v172
	v_max3_f32 v209, v209, v173, v162
	v_max3_f32 v209, v209, v163, v164
	v_bfe_u32 v232, v198, 0, 8
	v_lshl_add_u32 v232, v232, 6, v203
	ds_read_b32 v232, v232
	v_bfe_u32 v233, v198, 8, 8
	v_lshl_add_u32 v233, v233, 6, v203
	ds_read_b32 v233, v233
	v_bfe_u32 v234, v198, 16, 8
	v_lshl_add_u32 v234, v234, 6, v203
	ds_read_b32 v234, v234
	v_bfe_u32 v235, v198, 24, 8
	v_lshl_add_u32 v235, v235, 6, v203
	ds_read_b32 v235, v235
	v_bfe_u32 v236, v199, 0, 8
	v_lshl_add_u32 v236, v236, 6, v203
	ds_read_b32 v236, v236
	v_bfe_u32 v237, v199, 8, 8
	v_lshl_add_u32 v237, v237, 6, v203
	ds_read_b32 v237, v237
	v_bfe_u32 v238, v199, 16, 8
	v_lshl_add_u32 v238, v238, 6, v203
	ds_read_b32 v238, v238
	v_bfe_u32 v239, v199, 24, 8
	v_lshl_add_u32 v239, v239, 6, v203
	ds_read_b32 v239, v239
	s_waitcnt lgkmcnt(8)
	v_add_f32_e32 v165, v154, v240
	v_add_f32_e32 v154, v155, v241
	v_add_f32_e32 v155, v156, v246
	v_add_f32_e32 v156, v157, v247
	v_add_f32_e32 v157, v146, v248
	v_add_f32_e32 v146, v147, v249
	v_add_f32_e32 v147, v148, v250
	v_add_f32_e32 v148, v149, v251
	v_max3_f32 v209, v209, v165, v154
	v_max3_f32 v209, v209, v155, v156
	v_max3_f32 v209, v209, v157, v146
	v_max3_f32 v209, v209, v147, v148
	v_bfe_u32 v240, v230, 0, 8
	v_lshl_add_u32 v240, v240, 6, v203
	ds_read_b32 v240, v240
	v_bfe_u32 v241, v230, 8, 8
	v_lshl_add_u32 v241, v241, 6, v203
	ds_read_b32 v241, v241
	v_bfe_u32 v246, v230, 16, 8
	v_lshl_add_u32 v246, v246, 6, v203
	ds_read_b32 v246, v246
	v_bfe_u32 v247, v230, 24, 8
	v_lshl_add_u32 v247, v247, 6, v203
	ds_read_b32 v247, v247
	v_bfe_u32 v248, v231, 0, 8
	v_lshl_add_u32 v248, v248, 6, v203
	ds_read_b32 v248, v248
	v_bfe_u32 v249, v231, 8, 8
	v_lshl_add_u32 v249, v249, 6, v203
	ds_read_b32 v249, v249
	v_bfe_u32 v250, v231, 16, 8
	v_lshl_add_u32 v250, v250, 6, v203
	ds_read_b32 v250, v250
	v_bfe_u32 v251, v231, 24, 8
	v_lshl_add_u32 v251, v251, 6, v203
	ds_read_b32 v251, v251
	s_waitcnt lgkmcnt(8)
	v_add_f32_e32 v149, v142, v232
	v_add_f32_e32 v142, v143, v233
	v_add_f32_e32 v143, v144, v234
	v_add_f32_e32 v144, v145, v235
	v_add_f32_e32 v138, v138, v236
	v_add_f32_e32 v139, v139, v237
	v_add_f32_e32 v140, v140, v238
	v_add_f32_e32 v141, v141, v239
	v_max3_f32 v209, v209, v149, v142
	v_max3_f32 v209, v209, v143, v144
	v_max3_f32 v209, v209, v138, v139
	v_max3_f32 v209, v209, v140, v141
	s_waitcnt lgkmcnt(0)
	v_add_f32_e32 v145, v134, v240
	v_add_f32_e32 v134, v135, v241
	v_add_f32_e32 v135, v136, v246
	v_add_f32_e32 v136, v137, v247
	v_add_f32_e32 v130, v130, v248
	v_add_f32_e32 v131, v131, v249
	v_add_f32_e32 v137, v132, v250
	v_add_f32_e32 v202, v133, v251
	v_max3_f32 v209, v209, v145, v134
	v_max3_f32 v209, v209, v135, v136
	v_max3_f32 v209, v209, v130, v131
	v_mov_b32_e32 v133, v204
	v_max3_f32 v132, v209, v137, v202
	v_lshlrev_b32_e32 v133, 2, v133
	v_xor_b32_e32 v133, 64, v133
	ds_bpermute_b32 v133, v133, v132
	s_waitcnt lgkmcnt(0)
	v_max_f32_e32 v133, v133, v133
	v_max_f32_e32 v132, v132, v133
	v_mov_b32_e32 v133, v204
	s_nop 0
	v_lshlrev_b32_e32 v133, 2, v133
	v_xor_b32_e32 v133, 0x80, v133
	ds_bpermute_b32 v133, v133, v132
	s_waitcnt lgkmcnt(0)
	v_max_f32_e32 v133, v133, v133
	v_max_f32_e32 v203, v132, v133
	v_sub_f32_e32 v132, v190, v203
	v_exp_f32_e32 v132, v132
	v_sub_f32_e32 v133, v191, v203
	v_exp_f32_e32 v133, v133
	v_sub_f32_e32 v186, v186, v203
	v_add_f32_e32 v190, 0, v132
	v_exp_f32_e32 v186, v186
	v_add_f32_e32 v191, v133, v190
	v_sub_f32_e32 v190, v192, v203
	v_exp_f32_e32 v190, v190
	v_sub_f32_e32 v187, v187, v203
	v_exp_f32_e32 v187, v187
	v_sub_f32_e32 v188, v188, v203
	v_add_f32_e32 v192, v190, v191
	v_sub_f32_e32 v191, v193, v203
	v_exp_f32_e32 v191, v191
	v_sub_f32_e32 v182, v182, v203
	v_exp_f32_e32 v182, v182
	v_sub_f32_e32 v183, v183, v203
	v_add_f32_e32 v193, v191, v192
	v_sub_f32_e32 v192, v227, v203
	v_exp_f32_e32 v192, v192
	v_exp_f32_e32 v183, v183
	v_sub_f32_e32 v184, v184, v203
	v_exp_f32_e32 v184, v184
	v_add_f32_e32 v193, v192, v193
	v_add_f32_e32 v193, v186, v193
	v_add_f32_e32 v194, v187, v193
	v_exp_f32_e32 v193, v188
	v_sub_f32_e32 v188, v189, v203
	v_exp_f32_e32 v188, v188
	v_sub_f32_e32 v185, v185, v203
	v_add_f32_e32 v194, v193, v194
	v_exp_f32_e32 v185, v185
	v_add_f32_e32 v189, v188, v194
	v_sub_f32_e32 v178, v178, v203
	v_add_f32_e32 v189, v182, v189
	v_exp_f32_e32 v178, v178
	v_sub_f32_e32 v179, v179, v203
	v_add_f32_e32 v189, v183, v189
	v_exp_f32_e32 v179, v179
	v_sub_f32_e32 v180, v180, v203
	v_add_f32_e32 v189, v184, v189
	v_exp_f32_e32 v180, v180
	v_sub_f32_e32 v181, v181, v203
	v_add_f32_e32 v189, v185, v189
	v_exp_f32_e32 v181, v181
	v_sub_f32_e32 v174, v174, v203
	v_add_f32_e32 v189, v178, v189
	v_exp_f32_e32 v174, v174
	v_sub_f32_e32 v175, v175, v203
	v_add_f32_e32 v189, v179, v189
	v_exp_f32_e32 v175, v175
	v_sub_f32_e32 v176, v176, v203
	v_add_f32_e32 v189, v180, v189
	v_exp_f32_e32 v176, v176
	v_sub_f32_e32 v177, v177, v203
	v_add_f32_e32 v189, v181, v189
	v_exp_f32_e32 v177, v177
	v_sub_f32_e32 v166, v166, v203
	v_add_f32_e32 v189, v174, v189
	v_exp_f32_e32 v166, v166
	v_sub_f32_e32 v167, v167, v203
	v_add_f32_e32 v189, v175, v189
	v_exp_f32_e32 v167, v167
	v_sub_f32_e32 v168, v168, v203
	v_add_f32_e32 v189, v176, v189
	v_exp_f32_e32 v168, v168
	v_sub_f32_e32 v169, v169, v203
	v_add_f32_e32 v189, v177, v189
	v_exp_f32_e32 v169, v169
	v_sub_f32_e32 v158, v158, v203
; DI float shx(float v, int m) { return __int_as_float(__builtin_amdgcn_ds_bpermute((lane_now() ^ m) << 2, __float_as_int(v))); }
; DI int shx(int v, int m) { return __builtin_amdgcn_ds_bpermute((lane_now() ^ m) << 2, v); }
; DI float shidx(float v, int src) { return __int_as_float(__builtin_amdgcn_ds_bpermute(src << 2, __float_as_int(v))); }
; DI int shidx(int v, int src) { return __builtin_amdgcn_ds_bpermute(src << 2, v); }
; DI u16 f2bf(float x) { return (u16)(pk2bf(x, 0.f) & 0xffffu); }
; DI void phase_mix_b2(int wv_, int vb_, int nvb_, char* ws_, const Ctx& p, char* smem) {
;     ...
;     float sum = 0.f;
; #pragma unroll
;     for (int kb = 0; kb < 16; ++kb)
; #pragma unroll
;       for (int i = 0; i < 4; ++i) { float pv = __builtin_amdgcn_exp2f(lg[kb][i] - mx); lg[kb][i] = pv; sum += pv; }
;     sum += shx(sum, 16); sum += shx(sum, 32);
;     bf16x8 pall[8];
; #pragma unroll
;     for (int q = 0; q < 8; ++q)
; #pragma unroll
;       for (int j = 0; j < 4; ++j) { pall[q][j] = (short)f2bf(lg[2 * q][j]); pall[q][4 + j] = (short)f2bf(lg[2 * q + 1][j]); }
;     char* Vs = smem + wave * 16384;
;     float invs[4];
; #pragma unroll
;     for (int i = 0; i < 4; ++i) invs[i] = 1.0f / shidx(sum, i);
;     f32x4 oacc[4];
; #pragma unroll
;     for (int cb = 0; cb < 4; ++cb) oacc[cb] = (f32x4){0.f, 0.f, 0.f, 0.f};
; #pragma unroll
;     for (int sh = 0; sh < 2; ++sh) {
;       asm volatile("s_waitcnt lgkmcnt(0)" ::: "memory");
; #pragma unroll
;       for (int rr = 0; rr < 16; ++rr) {
;         const int row = rr * 8 + (lane >> 3), piece = lane & 7;
;         *(bf16x8*)(Vs + row * 128 + (((piece >> 1) ^ ((row >> 1) & 3)) * 32) + (piece & 1) * 16) = (sh == 0) ? vreg[rr] : vreg2[rr];
	v_add_f32_e32 v189, v166, v189
	v_exp_f32_e32 v194, v158
	v_add_f32_e32 v189, v167, v189
	v_add_f32_e32 v189, v168, v189
	v_add_f32_e32 v189, v169, v189
	v_sub_f32_e32 v159, v159, v203
	v_add_f32_e32 v158, v194, v189
	v_exp_f32_e32 v189, v159
	v_sub_f32_e32 v159, v160, v203
	v_exp_f32_e32 v195, v159
	v_sub_f32_e32 v159, v161, v203
	v_exp_f32_e32 v196, v159
	v_sub_f32_e32 v150, v150, v203
	v_exp_f32_e32 v197, v150
	v_sub_f32_e32 v151, v151, v203
	v_add_f32_e32 v158, v189, v158
	v_exp_f32_e32 v198, v151
	v_sub_f32_e32 v151, v152, v203
	v_add_f32_e32 v158, v195, v158
	v_exp_f32_e32 v199, v151
	v_sub_f32_e32 v151, v170, v203
	v_add_f32_e32 v158, v196, v158
	v_exp_f32_e32 v170, v151
	v_sub_f32_e32 v151, v153, v203
	v_add_f32_e32 v150, v197, v158
	v_exp_f32_e32 v227, v151
	v_sub_f32_e32 v151, v171, v203
	v_add_f32_e32 v150, v198, v150
	v_exp_f32_e32 v171, v151
	v_sub_f32_e32 v151, v172, v203
	v_add_f32_e32 v150, v199, v150
	v_exp_f32_e32 v172, v151
	v_sub_f32_e32 v151, v173, v203
	v_add_f32_e32 v150, v170, v150
	v_exp_f32_e32 v173, v151
	v_sub_f32_e32 v151, v162, v203
	v_add_f32_e32 v150, v227, v150
	v_exp_f32_e32 v162, v151
	v_sub_f32_e32 v151, v163, v203
	v_add_f32_e32 v150, v171, v150
	v_exp_f32_e32 v163, v151
	v_sub_f32_e32 v151, v164, v203
	v_add_f32_e32 v150, v172, v150
	v_exp_f32_e32 v164, v151
	v_sub_f32_e32 v151, v165, v203
	v_add_f32_e32 v150, v173, v150
	v_exp_f32_e32 v165, v151
	v_sub_f32_e32 v151, v154, v203
	v_add_f32_e32 v150, v162, v150
	v_exp_f32_e32 v228, v151
	v_sub_f32_e32 v151, v155, v203
	v_add_f32_e32 v150, v163, v150
	v_exp_f32_e32 v229, v151
	v_sub_f32_e32 v151, v156, v203
	v_add_f32_e32 v150, v164, v150
	v_exp_f32_e32 v230, v151
	v_sub_f32_e32 v151, v157, v203
	v_add_f32_e32 v150, v165, v150
	v_exp_f32_e32 v231, v151
	v_sub_f32_e32 v146, v146, v203
	v_add_f32_e32 v150, v228, v150
	v_exp_f32_e32 v232, v146
	v_sub_f32_e32 v147, v147, v203
	v_add_f32_e32 v150, v229, v150
	v_exp_f32_e32 v233, v147
	v_sub_f32_e32 v147, v148, v203
	v_add_f32_e32 v150, v230, v150
	v_exp_f32_e32 v234, v147
	v_sub_f32_e32 v147, v149, v203
	v_add_f32_e32 v150, v231, v150
	v_exp_f32_e32 v235, v147
	v_sub_f32_e32 v142, v142, v203
	v_add_f32_e32 v146, v232, v150
	v_exp_f32_e32 v236, v142
	v_sub_f32_e32 v143, v143, v203
	v_add_f32_e32 v146, v233, v146
	v_exp_f32_e32 v237, v143
	v_sub_f32_e32 v143, v144, v203
	v_add_f32_e32 v146, v234, v146
	v_exp_f32_e32 v238, v143
	v_sub_f32_e32 v138, v138, v203
	v_add_f32_e32 v146, v235, v146
	v_exp_f32_e32 v239, v138
	v_sub_f32_e32 v139, v139, v203
	v_add_f32_e32 v142, v236, v146
	v_exp_f32_e32 v240, v139
	v_sub_f32_e32 v139, v140, v203
	v_add_f32_e32 v142, v237, v142
	v_exp_f32_e32 v241, v139
	v_sub_f32_e32 v139, v141, v203
	v_add_f32_e32 v142, v238, v142
	v_exp_f32_e32 v246, v139
	v_sub_f32_e32 v139, v145, v203
	v_add_f32_e32 v138, v239, v142
	v_exp_f32_e32 v247, v139
	v_sub_f32_e32 v134, v134, v203
	v_add_f32_e32 v138, v240, v138
	v_exp_f32_e32 v248, v134
	v_sub_f32_e32 v135, v135, v203
	v_add_f32_e32 v138, v241, v138
	v_exp_f32_e32 v249, v135
	v_sub_f32_e32 v135, v136, v203
	v_add_f32_e32 v138, v246, v138
	v_exp_f32_e32 v250, v135
	v_sub_f32_e32 v130, v130, v203
	v_add_f32_e32 v138, v247, v138
	v_exp_f32_e32 v130, v130
	v_sub_f32_e32 v131, v131, v203
	v_add_f32_e32 v134, v248, v138
	v_exp_f32_e32 v131, v131
	v_sub_f32_e32 v135, v137, v203
	v_add_f32_e32 v134, v249, v134
	v_exp_f32_e32 v251, v135
	v_sub_f32_e32 v135, v202, v203
	v_add_f32_e32 v134, v250, v134
	v_exp_f32_e32 v202, v135
	v_add_f32_e32 v134, v130, v134
	v_mov_b32_e32 v135, v204
	v_add_f32_e32 v134, v131, v134
	v_add_f32_e32 v134, v251, v134
	v_lshlrev_b32_e32 v135, 2, v135
	v_add_f32_e32 v134, v202, v134
	v_xor_b32_e32 v135, 64, v135
	ds_bpermute_b32 v135, v135, v134
	v_cvt_pk_bf16_f32 v144, v173, v162
	v_cvt_pk_bf16_f32 v145, v163, v164
	v_cvt_pk_bf16_f32 v138, v165, v228
	v_and_b32_e32 v165, 16, v224
	s_waitcnt lgkmcnt(0)
	v_add_f32_e32 v203, v134, v135
	v_mov_b32_e32 v134, v204
	v_cvt_pk_bf16_f32 v153, v167, v168
	v_lshlrev_b32_e32 v134, 2, v134
	v_xor_b32_e32 v134, 0x80, v134
	ds_bpermute_b32 v209, v134, v203
	v_cvt_pk_bf16_f32 v152, v177, v166
	v_lshlrev_b32_e32 v166, 3, v222
	s_waitcnt lgkmcnt(0)
	v_cvt_pk_bf16_f32 v161, v187, v193
	s_waitcnt lgkmcnt(0)
	v_add_f32_e32 v162, v203, v209
	v_cvt_pk_bf16_f32 v160, v192, v186
	v_readlane_b32 s0, v162, 0
	v_readlane_b32 s1, v162, 1
	v_readlane_b32 s8, v162, 2
	v_readlane_b32 s9, v162, 3
	v_lshlrev_b32_e32 v162, 4, v221
	v_and_b32_e32 v163, 0x380, v162
	v_lshrrev_b32_e32 v162, 1, v220
	v_xor_b32_e32 v162, v223, v162
	v_lshlrev_b32_e32 v162, 5, v162
	v_and_b32_e32 v162, 0x60, v162
	v_add_u32_e32 v164, v225, v162
	v_lshrrev_b32_e32 v162, 2, v0
	v_or_b32_e32 v162, v226, v162
	v_lshl_add_u32 v167, v162, 7, v225
	v_lshlrev_b32_e32 v162, 4, v162
	v_add3_u32 v163, v164, v165, v163
	v_and_or_b32 v166, v162, s6, v166
	s_waitcnt vmcnt(31)
	ds_write_b128 v163, v[18:21]
	s_waitcnt vmcnt(30)
	ds_write_b128 v163, v[22:25] offset:1024
	s_waitcnt vmcnt(29)
	ds_write_b128 v163, v[26:29] offset:2048
	s_waitcnt vmcnt(28)
	ds_write_b128 v163, v[30:33] offset:3072
	s_waitcnt vmcnt(27)
	ds_write_b128 v163, v[42:45] offset:4096
	s_waitcnt vmcnt(26)
	ds_write_b128 v163, v[50:53] offset:5120
	s_waitcnt vmcnt(25)
	ds_write_b128 v163, v[54:57] offset:6144
	s_waitcnt vmcnt(24)
	ds_write_b128 v163, v[62:65] offset:7168
	s_waitcnt vmcnt(23)
	ds_write_b128 v163, v[74:77] offset:8192
	s_waitcnt vmcnt(22)
	ds_write_b128 v163, v[82:85] offset:9216
	s_waitcnt vmcnt(21)
	ds_write_b128 v163, v[90:93] offset:10240
	s_waitcnt vmcnt(20)
	ds_write_b128 v163, v[98:101] offset:11264
	s_waitcnt vmcnt(19)
; #define MFMA16(a, b, c) __builtin_amdgcn_mfma_f32_16x16x32_bf16((a), (b), (c), 0, 0, 0)
; DI void phase_mix_b2(int wv_, int vb_, int nvb_, char* ws_, const Ctx& p, char* smem) {
;     ...
; #pragma unroll
;     for (int sh = 0; sh < 2; ++sh) {
;       asm volatile("s_waitcnt lgkmcnt(0)" ::: "memory");
; #pragma unroll
;       for (int rr = 0; rr < 16; ++rr) {
;         const int row = rr * 8 + (lane >> 3), piece = lane & 7;
;         *(bf16x8*)(Vs + row * 128 + (((piece >> 1) ^ ((row >> 1) & 3)) * 32) + (piece & 1) * 16) = (sh == 0) ? vreg[rr] : vreg2[rr];
;       }
;       asm volatile("s_waitcnt lgkmcnt(0)" ::: "memory");
; #pragma unroll
;       for (int ks = 0; ks < 4; ++ks) {
;         const bf16x8 pa = pall[sh * 4 + ks];
;         const int rlo = ks * 32 + fq * 4 + (n16 >> 2);
;         const int sw = (rlo >> 1) & 3;
; #pragma unroll
;         for (int cb = 0; cb < 4; ++cb) {
;           const int off = ((cb ^ sw) * 32) + (n16 & 3) * 8;
;           s16x4 lo = __builtin_amdgcn_ds_read_tr16_b64_v4i16((__attribute__((address_space(3))) s16x4*)(Vs + rlo * 128 + off));
;           s16x4 hi = __builtin_amdgcn_ds_read_tr16_b64_v4i16((__attribute__((address_space(3))) s16x4*)(Vs + (16 + rlo) * 128 + off));
;           bf16x8 vb = __builtin_shufflevector(lo, hi, 0, 1, 2, 3, 4, 5, 6, 7);
;           oacc[cb] = MFMA16(pa, vb, oacc[cb]);
;         }
;       }
;     }
	ds_write_b128 v163, v[106:109] offset:12288
	s_waitcnt vmcnt(18)
	ds_write_b128 v163, v[114:117] offset:13312
	s_waitcnt vmcnt(17)
	ds_write_b128 v163, v[122:125] offset:14336
	s_waitcnt vmcnt(16)
	ds_write_b128 v163, v[126:129] offset:15360
	v_add_u32_e32 v162, v167, v166
	s_waitcnt lgkmcnt(0)
	v_cvt_pk_bf16_f32 v159, v190, v191
	v_cvt_pk_bf16_f32 v158, v132, v133
	ds_read_b64_tr_b16 v[18:19], v162
	ds_read_b64_tr_b16 v[20:21], v162 offset:2048
	s_waitcnt lgkmcnt(0)
	v_mfma_f32_16x16x32_bf16 v[22:25], v[158:161], v[18:21], 0
	v_xad_u32 v20, v166, 32, v167
	v_xad_u32 v19, v166, 64, v167
	v_xad_u32 v18, v166, s6, v167
	v_cvt_pk_bf16_f32 v157, v179, v180
	v_cvt_pk_bf16_f32 v156, v185, v178
	v_cvt_pk_bf16_f32 v155, v183, v184
	v_cvt_pk_bf16_f32 v154, v188, v182
	ds_read_b64_tr_b16 v[26:27], v20
	ds_read_b64_tr_b16 v[28:29], v20 offset:2048
	ds_read_b64_tr_b16 v[30:31], v19
	ds_read_b64_tr_b16 v[32:33], v19 offset:2048
	ds_read_b64_tr_b16 v[42:43], v18
	ds_read_b64_tr_b16 v[44:45], v18 offset:2048
	ds_read_b64_tr_b16 v[50:51], v162 offset:4096
	ds_read_b64_tr_b16 v[52:53], v162 offset:6144
	s_waitcnt lgkmcnt(0)
	v_mfma_f32_16x16x32_bf16 v[22:25], v[154:157], v[50:53], v[22:25]
	ds_read_b64_tr_b16 v[50:51], v20 offset:4096
	ds_read_b64_tr_b16 v[52:53], v20 offset:6144
	v_cvt_pk_bf16_f32 v151, v175, v176
	v_cvt_pk_bf16_f32 v150, v181, v174
	v_mfma_f32_16x16x32_bf16 v[26:29], v[158:161], v[26:29], 0
	v_cvt_pk_bf16_f32 v149, v198, v199
	v_cvt_pk_bf16_f32 v148, v196, v197
	v_cvt_pk_bf16_f32 v147, v189, v195
	s_waitcnt lgkmcnt(0)
	v_mfma_f32_16x16x32_bf16 v[26:29], v[154:157], v[50:53], v[26:29]
	ds_read_b64_tr_b16 v[50:51], v19 offset:4096
	ds_read_b64_tr_b16 v[52:53], v19 offset:6144
	v_cvt_pk_bf16_f32 v146, v169, v194
	v_cvt_pk_bf16_f32 v143, v171, v172
	v_mfma_f32_16x16x32_bf16 v[30:33], v[158:161], v[30:33], 0
	v_cvt_pk_bf16_f32 v142, v170, v227
	v_cvt_pk_bf16_f32 v141, v233, v234
	v_cvt_pk_bf16_f32 v140, v231, v232
	s_waitcnt lgkmcnt(0)
	v_mfma_f32_16x16x32_bf16 v[30:33], v[154:157], v[50:53], v[30:33]
	ds_read_b64_tr_b16 v[50:51], v18 offset:4096
	ds_read_b64_tr_b16 v[52:53], v18 offset:6144
	v_cvt_pk_bf16_f32 v139, v229, v230
	v_cvt_pk_bf16_f32 v137, v241, v246
	v_mfma_f32_16x16x32_bf16 v[42:45], v[158:161], v[42:45], 0
	v_cvt_pk_bf16_f32 v136, v239, v240
	v_cvt_pk_bf16_f32 v135, v237, v238
	v_cvt_pk_bf16_f32 v134, v235, v236
	s_waitcnt lgkmcnt(0)
	v_mfma_f32_16x16x32_bf16 v[42:45], v[154:157], v[50:53], v[42:45]
	ds_read_b64_tr_b16 v[50:51], v162 offset:8192
	ds_read_b64_tr_b16 v[52:53], v162 offset:10240
	v_cvt_pk_bf16_f32 v133, v251, v202
	v_cvt_pk_bf16_f32 v132, v130, v131
	s_waitcnt lgkmcnt(0)
	v_mfma_f32_16x16x32_bf16 v[22:25], v[150:153], v[50:53], v[22:25]
	ds_read_b64_tr_b16 v[50:51], v20 offset:8192
	ds_read_b64_tr_b16 v[52:53], v20 offset:10240
	v_cvt_pk_bf16_f32 v131, v249, v250
	v_cvt_pk_bf16_f32 v130, v247, v248
	s_waitcnt lgkmcnt(0)
	v_mfma_f32_16x16x32_bf16 v[26:29], v[150:153], v[50:53], v[26:29]
	ds_read_b64_tr_b16 v[50:51], v19 offset:8192
	ds_read_b64_tr_b16 v[52:53], v19 offset:10240
	s_waitcnt lgkmcnt(0)
	v_mfma_f32_16x16x32_bf16 v[30:33], v[150:153], v[50:53], v[30:33]
	ds_read_b64_tr_b16 v[50:51], v18 offset:8192
	ds_read_b64_tr_b16 v[52:53], v18 offset:10240
	s_waitcnt lgkmcnt(0)
	v_mfma_f32_16x16x32_bf16 v[42:45], v[150:153], v[50:53], v[42:45]
	ds_read_b64_tr_b16 v[50:51], v162 offset:12288
	ds_read_b64_tr_b16 v[52:53], v162 offset:14336
	s_waitcnt lgkmcnt(0)
	v_mfma_f32_16x16x32_bf16 v[22:25], v[146:149], v[50:53], v[22:25]
	ds_read_b64_tr_b16 v[50:51], v20 offset:12288
	ds_read_b64_tr_b16 v[52:53], v20 offset:14336
	s_waitcnt lgkmcnt(0)
	v_mfma_f32_16x16x32_bf16 v[26:29], v[146:149], v[50:53], v[26:29]
	ds_read_b64_tr_b16 v[50:51], v19 offset:12288
	ds_read_b64_tr_b16 v[52:53], v19 offset:14336
	s_waitcnt lgkmcnt(0)
	v_mfma_f32_16x16x32_bf16 v[30:33], v[146:149], v[50:53], v[30:33]
	ds_read_b64_tr_b16 v[50:51], v18 offset:12288
	ds_read_b64_tr_b16 v[52:53], v18 offset:14336
	s_waitcnt lgkmcnt(0)
	s_waitcnt vmcnt(15)
	ds_write_b128 v163, v[2:5]
	s_waitcnt vmcnt(14)
	ds_write_b128 v163, v[6:9] offset:1024
	s_waitcnt vmcnt(13)
	ds_write_b128 v163, v[10:13] offset:2048
	s_waitcnt vmcnt(12)
	ds_write_b128 v163, v[14:17] offset:3072
	s_waitcnt vmcnt(11)
	ds_write_b128 v163, v[34:37] offset:4096
	s_waitcnt vmcnt(10)
	ds_write_b128 v163, v[38:41] offset:5120
	s_waitcnt vmcnt(9)
	ds_write_b128 v163, v[46:49] offset:6144
	s_waitcnt vmcnt(8)
	ds_write_b128 v163, v[58:61] offset:7168
	s_waitcnt vmcnt(7)
	ds_write_b128 v163, v[66:69] offset:8192
	s_waitcnt vmcnt(6)
	ds_write_b128 v163, v[70:73] offset:9216
	s_waitcnt vmcnt(5)
	ds_write_b128 v163, v[78:81] offset:10240
	s_waitcnt vmcnt(4)
	ds_write_b128 v163, v[86:89] offset:11264
	s_waitcnt vmcnt(3)
	ds_write_b128 v163, v[94:97] offset:12288
	s_waitcnt vmcnt(2)
	ds_write_b128 v163, v[102:105] offset:13312
	s_waitcnt vmcnt(1)
	ds_write_b128 v163, v[110:113] offset:14336
	s_waitcnt vmcnt(0)
	ds_write_b128 v163, v[118:121] offset:15360
	s_waitcnt lgkmcnt(0)
	ds_read_b64_tr_b16 v[2:3], v162
	ds_read_b64_tr_b16 v[4:5], v162 offset:2048
	s_waitcnt lgkmcnt(0)
	v_mfma_f32_16x16x32_bf16 v[2:5], v[142:145], v[2:5], v[22:25]
	ds_read_b64_tr_b16 v[6:7], v20
	ds_read_b64_tr_b16 v[8:9], v20 offset:2048
	ds_read_b64_tr_b16 v[10:11], v19
	ds_read_b64_tr_b16 v[12:13], v19 offset:2048
	ds_read_b64_tr_b16 v[14:15], v18
	ds_read_b64_tr_b16 v[16:17], v18 offset:2048
	ds_read_b64_tr_b16 v[22:23], v162 offset:4096
	ds_read_b64_tr_b16 v[24:25], v162 offset:6144
	s_waitcnt lgkmcnt(0)
; #define MFMA16(a, b, c) __builtin_amdgcn_mfma_f32_16x16x32_bf16((a), (b), (c), 0, 0, 0)
; DI u16 f2bf(float x) { return (u16)(pk2bf(x, 0.f) & 0xffffu); }
; DI void phase_mix_b2(int wv_, int vb_, int nvb_, char* ws_, const Ctx& p, char* smem) {
;     ...
;       for (int ks = 0; ks < 4; ++ks) {
;         const bf16x8 pa = pall[sh * 4 + ks];
;         const int rlo = ks * 32 + fq * 4 + (n16 >> 2);
;         const int sw = (rlo >> 1) & 3;
; #pragma unroll
;         for (int cb = 0; cb < 4; ++cb) {
;           const int off = ((cb ^ sw) * 32) + (n16 & 3) * 8;
;           s16x4 lo = __builtin_amdgcn_ds_read_tr16_b64_v4i16((__attribute__((address_space(3))) s16x4*)(Vs + rlo * 128 + off));
;           s16x4 hi = __builtin_amdgcn_ds_read_tr16_b64_v4i16((__attribute__((address_space(3))) s16x4*)(Vs + (16 + rlo) * 128 + off));
;           bf16x8 vb = __builtin_shufflevector(lo, hi, 0, 1, 2, 3, 4, 5, 6, 7);
;           oacc[cb] = MFMA16(pa, vb, oacc[cb]);
;         }
;       }
;     }
;     ...
;     if (fq == 0) {
;       u16* yp = Y + qrow * 1024 + hkv * 256;
; #pragma unroll
;       for (int i = 0; i < 4; ++i)
; #pragma unroll
;         for (int cb = 0; cb < 4; ++cb) yp[i * 64 + cb * 16 + n16] = f2bf(oacc[cb][i] * invs[i]);
;     }
	v_mfma_f32_16x16x32_bf16 v[2:5], v[138:141], v[22:25], v[2:5]
	ds_read_b64_tr_b16 v[22:23], v20 offset:4096
	ds_read_b64_tr_b16 v[24:25], v20 offset:6144
	v_mfma_f32_16x16x32_bf16 v[6:9], v[142:145], v[6:9], v[26:29]
	s_waitcnt lgkmcnt(0)
	v_mfma_f32_16x16x32_bf16 v[6:9], v[138:141], v[22:25], v[6:9]
	ds_read_b64_tr_b16 v[22:23], v19 offset:4096
	ds_read_b64_tr_b16 v[24:25], v19 offset:6144
	v_mfma_f32_16x16x32_bf16 v[10:13], v[142:145], v[10:13], v[30:33]
	v_mfma_f32_16x16x32_bf16 v[42:45], v[146:149], v[50:53], v[42:45]
	s_waitcnt lgkmcnt(0)
	v_mfma_f32_16x16x32_bf16 v[10:13], v[138:141], v[22:25], v[10:13]
	ds_read_b64_tr_b16 v[22:23], v18 offset:4096
	ds_read_b64_tr_b16 v[24:25], v18 offset:6144
	v_mfma_f32_16x16x32_bf16 v[14:17], v[142:145], v[14:17], v[42:45]
	s_waitcnt lgkmcnt(0)
	v_mfma_f32_16x16x32_bf16 v[14:17], v[138:141], v[22:25], v[14:17]
	ds_read_b64_tr_b16 v[22:23], v162 offset:8192
	ds_read_b64_tr_b16 v[24:25], v162 offset:10240
	s_waitcnt lgkmcnt(0)
	v_mfma_f32_16x16x32_bf16 v[2:5], v[134:137], v[22:25], v[2:5]
	ds_read_b64_tr_b16 v[22:23], v20 offset:8192
	ds_read_b64_tr_b16 v[24:25], v20 offset:10240
	s_waitcnt lgkmcnt(0)
	v_mfma_f32_16x16x32_bf16 v[6:9], v[134:137], v[22:25], v[6:9]
	ds_read_b64_tr_b16 v[22:23], v19 offset:8192
	ds_read_b64_tr_b16 v[24:25], v19 offset:10240
	s_waitcnt lgkmcnt(0)
	v_mfma_f32_16x16x32_bf16 v[10:13], v[134:137], v[22:25], v[10:13]
	ds_read_b64_tr_b16 v[22:23], v18 offset:8192
	ds_read_b64_tr_b16 v[24:25], v18 offset:10240
	s_waitcnt lgkmcnt(0)
	v_mfma_f32_16x16x32_bf16 v[14:17], v[134:137], v[22:25], v[14:17]
	ds_read_b64_tr_b16 v[22:23], v162 offset:12288
	ds_read_b64_tr_b16 v[24:25], v162 offset:14336
	s_waitcnt lgkmcnt(0)
	v_mfma_f32_16x16x32_bf16 v[2:5], v[130:133], v[22:25], v[2:5]
	ds_read_b64_tr_b16 v[22:23], v20 offset:12288
	ds_read_b64_tr_b16 v[24:25], v20 offset:14336
	s_waitcnt lgkmcnt(0)
	v_mfma_f32_16x16x32_bf16 v[6:9], v[130:133], v[22:25], v[6:9]
	ds_read_b64_tr_b16 v[20:21], v19 offset:12288
	ds_read_b64_tr_b16 v[22:23], v19 offset:14336
	s_waitcnt lgkmcnt(0)
	v_mfma_f32_16x16x32_bf16 v[10:13], v[130:133], v[20:23], v[10:13]
	ds_read_b64_tr_b16 v[20:21], v18 offset:12288
	ds_read_b64_tr_b16 v[22:23], v18 offset:14336
	s_waitcnt lgkmcnt(0)
	v_mfma_f32_16x16x32_bf16 v[14:17], v[130:133], v[20:23], v[14:17]
	s_and_saveexec_b64 s[6:7], vcc
	s_cbranch_execz .LBB0_352
	v_div_scale_f32 v18, s[14:15], s9, s9, 1.0
	v_rcp_f32_e32 v19, v18
	v_lshlrev_b32_e32 v0, 1, v0
	v_fma_f32 v20, -v18, v19, 1.0
	v_fmac_f32_e32 v19, v20, v19
	v_div_scale_f32 v20, vcc, 1.0, s9, 1.0
	v_mul_f32_e32 v21, v20, v19
	v_fma_f32 v22, -v18, v21, v20
	v_fmac_f32_e32 v21, v22, v19
	v_fma_f32 v18, -v18, v21, v20
	v_div_fmas_f32 v18, v18, v19, v21
	v_div_fixup_f32 v20, v18, s9, 1.0
	v_div_scale_f32 v18, s[14:15], s8, s8, 1.0
	v_rcp_f32_e32 v19, v18
	s_nop 0
	v_fma_f32 v21, -v18, v19, 1.0
	v_fmac_f32_e32 v19, v21, v19
	v_div_scale_f32 v21, vcc, 1.0, s8, 1.0
	v_mul_f32_e32 v22, v21, v19
	v_fma_f32 v23, -v18, v22, v21
	v_fmac_f32_e32 v22, v23, v19
	v_fma_f32 v18, -v18, v22, v21
	v_div_fmas_f32 v18, v18, v19, v22
	v_div_fixup_f32 v21, v18, s8, 1.0
	v_div_scale_f32 v18, s[8:9], s1, s1, 1.0
	v_rcp_f32_e32 v19, v18
	s_nop 0
	v_fma_f32 v22, -v18, v19, 1.0
	v_fmac_f32_e32 v19, v22, v19
	v_div_scale_f32 v22, vcc, 1.0, s1, 1.0
	v_mul_f32_e32 v23, v22, v19
	v_fma_f32 v24, -v18, v23, v22
	v_fmac_f32_e32 v23, v24, v19
	v_fma_f32 v18, -v18, v23, v22
	v_div_fmas_f32 v18, v18, v19, v23
	v_div_fixup_f32 v22, v18, s1, 1.0
	v_div_scale_f32 v18, s[8:9], s0, s0, 1.0
	v_rcp_f32_e32 v19, v18
	s_nop 0
	v_fma_f32 v23, -v18, v19, 1.0
	v_fmac_f32_e32 v19, v23, v19
	v_div_scale_f32 v23, vcc, 1.0, s0, 1.0
	v_mul_f32_e32 v24, v23, v19
	v_fma_f32 v25, -v18, v24, v23
	v_fmac_f32_e32 v24, v25, v19
	v_fma_f32 v18, -v18, v24, v23
	v_div_fmas_f32 v18, v18, v19, v24
	v_div_fixup_f32 v23, v18, s0, 1.0
	v_lshlrev_b64 v[18:19], 11, v[200:201]
	s_lshl_b32 s0, s12, 8
	v_lshl_add_u64 v[18:19], s[82:83], 0, v[18:19]
	s_ashr_i32 s1, s0, 31
	v_lshl_add_u64 v[18:19], s[0:1], 1, v[18:19]
	v_lshl_add_u64 v[18:19], v[18:19], 0, v[0:1]
	v_mul_f32_e32 v0, v23, v6
	v_cvt_pk_bf16_f32 v0, v0, s0
	global_store_short v[18:19], v0, off offset:32
	v_mul_f32_e32 v0, v23, v10
	v_cvt_pk_bf16_f32 v0, v0, s0
	global_store_short v[18:19], v0, off offset:64
	v_mul_f32_e32 v0, v23, v14
	v_cvt_pk_bf16_f32 v0, v0, s0
	global_store_short v[18:19], v0, off offset:96
	v_mul_f32_e32 v0, v22, v3
	v_cvt_pk_bf16_f32 v0, v0, s0
	global_store_short v[18:19], v0, off offset:128
	v_mul_f32_e32 v0, v22, v7
	v_cvt_pk_bf16_f32 v0, v0, s0
	global_store_short v[18:19], v0, off offset:160
	v_mul_f32_e32 v0, v22, v11
	v_cvt_pk_bf16_f32 v0, v0, s0
	global_store_short v[18:19], v0, off offset:192
	v_mul_f32_e32 v0, v22, v15
	v_cvt_pk_bf16_f32 v0, v0, s0
	global_store_short v[18:19], v0, off offset:224
	v_mul_f32_e32 v0, v21, v4
	v_cvt_pk_bf16_f32 v0, v0, s0
	global_store_short v[18:19], v0, off offset:256
	v_mul_f32_e32 v0, v21, v8
	v_cvt_pk_bf16_f32 v0, v0, s0
	global_store_short v[18:19], v0, off offset:288
	v_mul_f32_e32 v0, v21, v12
	v_cvt_pk_bf16_f32 v0, v0, s0
	global_store_short v[18:19], v0, off offset:320
	v_mul_f32_e32 v0, v21, v16
	v_cvt_pk_bf16_f32 v0, v0, s0
	global_store_short v[18:19], v0, off offset:352
	v_mul_f32_e32 v0, v20, v5
	v_cvt_pk_bf16_f32 v0, v0, s0
	global_store_short v[18:19], v0, off offset:384
	v_mul_f32_e32 v0, v20, v9
	v_cvt_pk_bf16_f32 v0, v0, s0
	global_store_short v[18:19], v0, off offset:416
	v_mul_f32_e32 v0, v20, v13
	v_cvt_pk_bf16_f32 v0, v0, s0
	v_mul_f32_e32 v2, v23, v2
	global_store_short v[18:19], v0, off offset:448
	v_mul_f32_e32 v0, v20, v17
	v_cvt_pk_bf16_f32 v2, v2, s0
	v_cvt_pk_bf16_f32 v0, v0, s0
	global_store_short v[18:19], v2, off
	global_store_short v[18:19], v0, off offset:480
	s_branch .LBB0_352

; DI int t5_bucket(int dist) {
;   if (dist < 16) return dist;
;   float lp = logf((float)dist / 16.0f) / 4.852030263919617f * 16.0f;
;   int b = 16 + (int)lp;
;   return b < 31 ? b : 31;
; }
; DI void phase_attn_a(int wv_, int vb_, int nvb_, char* ws_, const Ctx& p, char* smem) {
;   u16* Vt = (u16*)smem;
;   float* sBias = (float*)(smem + 64 * 260 * 2);
;   const u16* P = (const u16*)(ws_ + WS_P);
;   const int tid = tidx(wv_), lane = tid & 63, wave = tid >> 6, c = lane & 31, h = lane >> 5;
;   for (int k_ = 0; k_ < (6144 + nvb_ - 1) / nvb_; ++k_) {
;     const int u = (vb_ + k_ * nvb_ < 6144) ? vb_ + k_ * nvb_ : 6143;
;     const int head = u & 7, g = (u >> 3) % 3, rest = u / 24, idx = rest & 31, b = rest >> 5;
;     const int dil = (g == 0) ? 1 : ((g == 1) ? 4 : 16);
;     const int nbper = 32 / dil, r = idx / nbper, nb = idx % nbper;
;     u16* Og = (g == 0) ? (u16*)(ws_ + WS_H) : ((g == 1) ? (u16*)(ws_ + WS_H + 32 * MiB) : (u16*)(ws_ + WS_E));
;     float* lse = (float*)(ws_ + WS_LSE) + (size_t)g * NTOK * 8;
;     if (tid <= 128) sBias[tid] = p.rel_bias[t5_bucket(tid * dil) * 40 + g * 8 + head] * 1.4426950408889634f;
.LBB0_493:
	v_writelane_b32 v255, s54, 5
	s_cmp_lt_i32 s23, 2
	s_mov_b64 s[2:3], -1
	v_writelane_b32 v255, s55, 6
	s_cbranch_scc1 .LBB0_764
	s_cmp_gt_i32 s23, 2
	s_cbranch_scc0 .LBB0_552
	v_readlane_b32 s2, v253, 27
	v_readlane_b32 s3, v253, 28
	s_mov_b32 s0, s33
	v_mov_b32_e32 v0, v204
	s_andn2_b64 vcc, exec, s[2:3]
	s_cbranch_vccnz .LBB0_551
	s_mov_b32 s60, s33
	v_readlane_b32 s35, v253, 26
	v_readlane_b32 s44, v254, 14
	v_readlane_b32 s45, v254, 56
	v_readlane_b32 s56, v254, 32
	v_readlane_b32 s57, v254, 33
	v_and_b32_e32 v196, 31, v204
	v_lshrrev_b32_e32 v197, 5, v204
	v_lshl_add_u32 v202, s60, 6, v204
	s_lshl_b32 s0, s60, 5
	v_add_u32_e32 v200, s0, v196
	v_lshlrev_b32_e32 v201, 4, v197
	v_lshlrev_b32_e32 v239, 3, v197
	v_add_u32_e32 v240, 0xc00, v201
	v_add_u32_e32 v241, 0xffffff80, v202
	v_lshl_add_u32 v203, v202, 1, v214
	v_mul_u32_u24_e32 v198, 0x208, v196
	v_add_u32_e32 v198, v198, v214
	s_lshl_b32 s1, s60, 6
	v_add_u32_e32 v198, s1, v198
	v_add_u32_e32 v209, v198, v239
	v_lshl_add_u32 v198, v196, 2, v214
	v_sub_u32_e32 v198, v198, v201
	v_add_u32_e32 v216, 0x10400, v198
	v_lshl_add_u32 v198, v202, 2, v214
	v_add_u32_e32 v217, 0x10400, v198
	v_add_u32_e32 v198, 0xffffffe1, v202
	v_cmp_gt_u32_e32 vcc, 0x81, v198
	s_mov_b64 s[66:67], vcc
	v_max_i32_e32 v198, 0, v198
	v_min_u32_e32 v198, 0x80, v198
	v_lshlrev_b32_e32 v199, 0, v198
	v_mov_b32_e32 v246, 16
	v_cmp_le_u32_e32 vcc, 22, v199
	s_nop 1
	v_addc_co_u32_e32 v246, vcc, 0, v246, vcc
	v_cmp_le_u32_e32 vcc, 30, v199
	s_nop 1
	v_addc_co_u32_e32 v246, vcc, 0, v246, vcc
	v_cmp_le_u32_e32 vcc, 40, v199
	s_nop 1
	v_addc_co_u32_e32 v246, vcc, 0, v246, vcc
	v_cmp_le_u32_e32 vcc, 54, v199
	s_nop 1
	v_addc_co_u32_e32 v246, vcc, 0, v246, vcc
	v_cmp_le_u32_e32 vcc, 0x49, v199
	s_nop 1
	v_addc_co_u32_e32 v246, vcc, 0, v246, vcc
	v_cmp_le_u32_e32 vcc, 0x63, v199
	s_nop 1
	v_addc_co_u32_e32 v246, vcc, 0, v246, vcc
	v_cmp_le_u32_e32 vcc, 0x86, v199
	s_nop 1
	v_addc_co_u32_e32 v246, vcc, 0, v246, vcc
	v_cmp_le_u32_e32 vcc, 0xb6, v199
	s_nop 1
	v_addc_co_u32_e32 v246, vcc, 0, v246, vcc
	v_cmp_le_u32_e32 vcc, 0xf6, v199
	s_nop 1
	v_addc_co_u32_e32 v246, vcc, 0, v246, vcc
	v_cmp_le_u32_e32 vcc, 0x14c, v199
	s_nop 1
	v_addc_co_u32_e32 v246, vcc, 0, v246, vcc
	v_cmp_le_u32_e32 vcc, 0x1c2, v199
	s_nop 1
	v_addc_co_u32_e32 v246, vcc, 0, v246, vcc
	v_cmp_le_u32_e32 vcc, 0x261, v199
	s_nop 1
	v_addc_co_u32_e32 v246, vcc, 0, v246, vcc
	v_cmp_le_u32_e32 vcc, 0x339, v199
	s_nop 1
	v_addc_co_u32_e32 v246, vcc, 0, v246, vcc
	v_cmp_le_u32_e32 vcc, 0x45d, v199
	s_nop 1
	v_addc_co_u32_e32 v246, vcc, 0, v246, vcc
	v_cmp_le_u32_e32 vcc, 0x5e9, v199
	s_nop 1
	v_addc_co_u32_e32 v246, vcc, 0, v246, vcc
	v_cmp_gt_u32_e32 vcc, 16, v199
	s_nop 1
	v_cndmask_b32_e32 v246, v246, v199, vcc
	v_mul_u32_u24_e32 v218, 0xa0, v246
	v_lshlrev_b32_e32 v199, 2, v198
	v_mov_b32_e32 v246, 16
	v_cmp_le_u32_e32 vcc, 22, v199
	s_nop 1
	v_addc_co_u32_e32 v246, vcc, 0, v246, vcc
	v_cmp_le_u32_e32 vcc, 30, v199
	s_nop 1
	v_addc_co_u32_e32 v246, vcc, 0, v246, vcc
	v_cmp_le_u32_e32 vcc, 40, v199
	s_nop 1
	v_addc_co_u32_e32 v246, vcc, 0, v246, vcc
	v_cmp_le_u32_e32 vcc, 54, v199
	s_nop 1
	v_addc_co_u32_e32 v246, vcc, 0, v246, vcc
	v_cmp_le_u32_e32 vcc, 0x49, v199
	s_nop 1
	v_addc_co_u32_e32 v246, vcc, 0, v246, vcc
	v_cmp_le_u32_e32 vcc, 0x63, v199
	s_nop 1
	v_addc_co_u32_e32 v246, vcc, 0, v246, vcc
	v_cmp_le_u32_e32 vcc, 0x86, v199
	s_nop 1
	v_addc_co_u32_e32 v246, vcc, 0, v246, vcc
	v_cmp_le_u32_e32 vcc, 0xb6, v199
	s_nop 1
	v_addc_co_u32_e32 v246, vcc, 0, v246, vcc
	v_cmp_le_u32_e32 vcc, 0xf6, v199
	s_nop 1
	v_addc_co_u32_e32 v246, vcc, 0, v246, vcc
	v_cmp_le_u32_e32 vcc, 0x14c, v199
	s_nop 1
	v_addc_co_u32_e32 v246, vcc, 0, v246, vcc
	v_cmp_le_u32_e32 vcc, 0x1c2, v199
	s_nop 1
	v_addc_co_u32_e32 v246, vcc, 0, v246, vcc
	v_cmp_le_u32_e32 vcc, 0x261, v199
	s_nop 1
	v_addc_co_u32_e32 v246, vcc, 0, v246, vcc
	v_cmp_le_u32_e32 vcc, 0x339, v199
	s_nop 1
	v_addc_co_u32_e32 v246, vcc, 0, v246, vcc
	v_cmp_le_u32_e32 vcc, 0x45d, v199
	s_nop 1
	v_addc_co_u32_e32 v246, vcc, 0, v246, vcc
	v_cmp_le_u32_e32 vcc, 0x5e9, v199
	s_nop 1
	v_addc_co_u32_e32 v246, vcc, 0, v246, vcc
	v_cmp_gt_u32_e32 vcc, 16, v199
	s_nop 1
	v_cndmask_b32_e32 v246, v246, v199, vcc
	v_mul_u32_u24_e32 v219, 0xa0, v246
	v_lshlrev_b32_e32 v199, 4, v198
	v_mov_b32_e32 v246, 16
	v_cmp_le_u32_e32 vcc, 22, v199
	s_nop 1
	v_addc_co_u32_e32 v246, vcc, 0, v246, vcc
	v_cmp_le_u32_e32 vcc, 30, v199
	s_nop 1
	v_addc_co_u32_e32 v246, vcc, 0, v246, vcc
	v_cmp_le_u32_e32 vcc, 40, v199
	s_nop 1
	v_addc_co_u32_e32 v246, vcc, 0, v246, vcc
	v_cmp_le_u32_e32 vcc, 54, v199
	s_nop 1
	v_addc_co_u32_e32 v246, vcc, 0, v246, vcc
	v_cmp_le_u32_e32 vcc, 0x49, v199
	s_nop 1
	v_addc_co_u32_e32 v246, vcc, 0, v246, vcc
	v_cmp_le_u32_e32 vcc, 0x63, v199
	s_nop 1
	v_addc_co_u32_e32 v246, vcc, 0, v246, vcc
	v_cmp_le_u32_e32 vcc, 0x86, v199
	s_nop 1
	v_addc_co_u32_e32 v246, vcc, 0, v246, vcc
	v_cmp_le_u32_e32 vcc, 0xb6, v199
	s_nop 1
	v_addc_co_u32_e32 v246, vcc, 0, v246, vcc
	v_cmp_le_u32_e32 vcc, 0xf6, v199
	s_nop 1
	v_addc_co_u32_e32 v246, vcc, 0, v246, vcc
	v_cmp_le_u32_e32 vcc, 0x14c, v199
	s_nop 1
	v_addc_co_u32_e32 v246, vcc, 0, v246, vcc
	v_cmp_le_u32_e32 vcc, 0x1c2, v199
	s_nop 1
	v_addc_co_u32_e32 v246, vcc, 0, v246, vcc
	v_cmp_le_u32_e32 vcc, 0x261, v199
	s_nop 1
	v_addc_co_u32_e32 v246, vcc, 0, v246, vcc
	v_cmp_le_u32_e32 vcc, 0x339, v199
	s_nop 1
	v_addc_co_u32_e32 v246, vcc, 0, v246, vcc
	v_cmp_le_u32_e32 vcc, 0x45d, v199
	s_nop 1
	v_addc_co_u32_e32 v246, vcc, 0, v246, vcc
	v_cmp_le_u32_e32 vcc, 0x5e9, v199
	s_nop 1
	v_addc_co_u32_e32 v246, vcc, 0, v246, vcc
	v_cmp_gt_u32_e32 vcc, 16, v199
	s_nop 1
; DI void phase_attn_a(int wv_, int vb_, int nvb_, char* ws_, const Ctx& p, char* smem) {
;     ...
;   for (int k_ = 0; k_ < (6144 + nvb_ - 1) / nvb_; ++k_) {
;     const int u = (vb_ + k_ * nvb_ < 6144) ? vb_ + k_ * nvb_ : 6143;
;     const int head = u & 7, g = (u >> 3) % 3, rest = u / 24, idx = rest & 31, b = rest >> 5;
;     const int dil = (g == 0) ? 1 : ((g == 1) ? 4 : 16);
;     const int nbper = 32 / dil, r = idx / nbper, nb = idx % nbper;
;     u16* Og = (g == 0) ? (u16*)(ws_ + WS_H) : ((g == 1) ? (u16*)(ws_ + WS_H + 32 * MiB) : (u16*)(ws_ + WS_E));
;     float* lse = (float*)(ws_ + WS_LSE) + (size_t)g * NTOK * 8;
;     if (tid <= 128) sBias[tid] = p.rel_bias[t5_bucket(tid * dil) * 40 + g * 8 + head] * 1.4426950408889634f;
;     {
;       const int kk = tid; const int ksub = nb * 128 - 128 + kk;
;       bf16x8 v[8];
;       if (ksub >= 0) {
;         const u16* vp = P + ((size_t)b * SEQ + (size_t)ksub * dil + r) * 4608 + 3072 + g * 512 + head * 64;
; #pragma unroll
;         for (int i = 0; i < 8; ++i) v[i] = *(const bf16x8*)(vp + i * 8);
;       } else {
; #pragma unroll
;         for (int i = 0; i < 8; ++i) v[i] = zero8();
;       }
; #pragma unroll
;       for (int i = 0; i < 8; ++i)
; #pragma unroll
;         for (int jj = 0; jj < 8; ++jj) Vt[(i * 8 + jj) * 260 + kk] = (u16)v[i][jj];
;     }
;     __syncthreads();
;     {
;       const int qi = 32 * wave + c;
;       const int qtok = (nb * 128 + qi) * dil + r;
;       const u16* qp = P + ((size_t)b * SEQ + qtok) * 4608 + g * 512 + head * 64;
;       bf16x8 qf[4];
; #pragma unroll
;       for (int ks = 0; ks < 4; ++ks) qf[ks] = *(const bf16x8*)(qp + ks * 16 + h * 8);
;       float mx = -INFINITY, sum = 0.f;
;       f32x16 oacc[2]; oacc[0] = zero16(); oacc[1] = zero16();
; #pragma unroll 1
;       for (int kb = 0; kb < 5; ++kb) {
;         const int kk = 32 * wave + 32 * kb + c; const int ksub0 = nb * 128 - 128 + kk;
;         bf16x8 kf[4];
;         if (ksub0 >= 0) {
;           const u16* kp = P + ((size_t)b * SEQ + (size_t)ksub0 * dil + r) * 4608 + 1536 + g * 512 + head * 64;
; #pragma unroll
;           for (int ks = 0; ks < 4; ++ks) kf[ks] = *(const bf16x8*)(kp + ks * 16 + h * 8);
	v_cndmask_b32_e32 v246, v246, v199, vcc
	v_mul_u32_u24_e32 v220, 0xa0, v246
	s_mov_b32 s64, 0
	s_mov_b32 s65, 0
	s_mov_b32 s0, 0
	s_mul_i32 s0, s0, s45
	s_add_i32 s0, s0, s44
	s_min_i32 s0, s0, 0x17ff
	s_and_b32 s1, s0, 7
	s_lshr_b32 s3, s0, 3
	s_mul_hi_u32 s63, s3, 0xaaaaaaab
	s_lshr_b32 s63, s63, 1
	s_mul_i32 s68, s63, 3
	s_sub_i32 s62, s3, s68
	s_and_b32 s69, s63, 31
	s_lshr_b32 s70, s63, 5
	s_lshl_b32 s10, s62, 1
	s_sub_i32 s71, 5, s10
	s_lshr_b32 s11, s69, s71
	s_lshr_b32 s72, 32, s10
	s_add_i32 s72, s72, -1
	s_and_b32 s72, s69, s72
	s_lshl_b32 s12, s72, 7
	s_sub_i32 s73, 4, s60
	s_lshl_b32 s73, 1, s73
	s_add_i32 s73, s73, -1
	s_cmp_eq_u32 s72, 0
	s_cselect_b32 s13, s73, 0
	s_mul_i32 s73, s70, 0x2400000
	s_lshl_b32 s74, s62, 10
	s_lshl_b32 s75, s1, 7
	s_add_i32 s73, s73, s74
	s_add_i32 s73, s73, s75
	s_add_u32 s8, s86, s73
	s_addc_u32 s9, s87, 0
	s_mov_b32 s73, 0x8600000
	s_cmp_eq_u32 s62, 0
	s_cselect_b32 s73, 0x6600000, s73
	s_cmp_eq_u32 s62, 2
	s_cselect_b32 s73, 0x1c600000, s73
	s_lshl_b32 s74, s70, 22
	s_add_i32 s73, s73, s74
	s_add_i32 s73, s73, s75
	s_add_u32 s14, s78, s73
	s_addc_u32 s15, s79, 0
	s_lshl_b32 s73, s62, 20
	s_lshl_b32 s74, s70, 17
	s_add_i32 s73, s73, s74
	s_lshl_b32 s74, s1, 2
	s_add_i32 s73, s73, s74
	s_add_i32 s73, s73, 0x1e600000
	s_add_u32 s18, s78, s73
	s_addc_u32 s19, s79, 0
	s_lshl_b32 s61, s62, 3
	s_add_i32 s61, s61, s1
	s_lshl_b32 s61, s61, 2
	v_add_u32_e32 v231, s12, v200
	v_lshlrev_b32_e32 v196, s10, v231
	v_add_u32_e32 v196, s11, v196
	v_lshl_add_u32 v226, v196, 10, v239
	v_lshlrev_b32_e32 v228, 5, v196
	v_mul_u32_u24_e32 v196, 0x2400, v196
	v_add_u32_e32 v232, v196, v201
	v_add_u32_e32 v223, s64, v203
	v_add_u32_e32 v224, s65, v217
	v_add_u32_e32 v230, s12, v241
	v_max_i32_e32 v230, 0, v230
	v_lshlrev_b32_e32 v230, s10, v230
	v_add_u32_e32 v230, s11, v230
	v_mul_u32_u24_e32 v230, 0x2400, v230
	v_add_u32_e32 v230, 0x1800, v230
	global_load_dwordx4 v[98:101], v230, s[8:9] offset:0
	global_load_dwordx4 v[102:105], v230, s[8:9] offset:16
	global_load_dwordx4 v[106:109], v230, s[8:9] offset:32
	global_load_dwordx4 v[110:113], v230, s[8:9] offset:48
	global_load_dwordx4 v[114:117], v230, s[8:9] offset:64
	global_load_dwordx4 v[118:121], v230, s[8:9] offset:80
	global_load_dwordx4 v[122:125], v230, s[8:9] offset:96
	global_load_dwordx4 v[126:129], v230, s[8:9] offset:112
	s_cmp_eq_u32 s62, 0
	s_cselect_b64 vcc, -1, 0
	v_cndmask_b32_e32 v196, v219, v218, vcc
	s_cmp_eq_u32 s62, 2
	s_cselect_b64 vcc, -1, 0
	v_cndmask_b32_e32 v196, v196, v220, vcc
	v_add_u32_e32 v196, s61, v196
	global_load_dword v229, v196, s[56:57]
	v_add_u32_e32 v246, 0xffffff80, v231
	v_max_i32_e32 v246, 0, v246
	v_lshlrev_b32_e32 v246, s10, v246
	v_add_u32_e32 v246, s11, v246
	v_mul_u32_u24_e32 v246, 0x2400, v246
	v_add_u32_e32 v246, v246, v240
	global_load_dwordx4 v[2:5], v246, s[8:9] offset:0
	global_load_dwordx4 v[6:9], v246, s[8:9] offset:32
	global_load_dwordx4 v[10:13], v246, s[8:9] offset:64
	global_load_dwordx4 v[14:17], v246, s[8:9] offset:96
	v_add_u32_e32 v246, 0xffffffa0, v231
	v_max_i32_e32 v246, 0, v246
	v_lshlrev_b32_e32 v246, s10, v246
	v_add_u32_e32 v246, s11, v246
	v_mul_u32_u24_e32 v246, 0x2400, v246
	v_add_u32_e32 v246, v246, v240
	global_load_dwordx4 v[18:21], v246, s[8:9] offset:0
	global_load_dwordx4 v[22:25], v246, s[8:9] offset:32
	global_load_dwordx4 v[26:29], v246, s[8:9] offset:64
	global_load_dwordx4 v[30:33], v246, s[8:9] offset:96
	v_add_u32_e32 v246, 0xffffffc0, v231
	v_max_i32_e32 v246, 0, v246
	v_lshlrev_b32_e32 v246, s10, v246
	v_add_u32_e32 v246, s11, v246
	v_mul_u32_u24_e32 v246, 0x2400, v246
	v_add_u32_e32 v246, v246, v240
	global_load_dwordx4 v[34:37], v246, s[8:9] offset:0
	global_load_dwordx4 v[38:41], v246, s[8:9] offset:32
	global_load_dwordx4 v[42:45], v246, s[8:9] offset:64
	global_load_dwordx4 v[46:49], v246, s[8:9] offset:96
	v_add_u32_e32 v246, 0xffffffe0, v231
	v_max_i32_e32 v246, 0, v246
	v_lshlrev_b32_e32 v246, s10, v246
	v_add_u32_e32 v246, s11, v246
	v_mul_u32_u24_e32 v246, 0x2400, v246
	v_add_u32_e32 v246, v246, v240
	global_load_dwordx4 v[50:53], v246, s[8:9] offset:0
	global_load_dwordx4 v[54:57], v246, s[8:9] offset:32
	global_load_dwordx4 v[58:61], v246, s[8:9] offset:64
	global_load_dwordx4 v[62:65], v246, s[8:9] offset:96
	v_mov_b32_e32 v246, v231
	v_max_i32_e32 v246, 0, v246
	v_lshlrev_b32_e32 v246, s10, v246
	v_add_u32_e32 v246, s11, v246
	v_mul_u32_u24_e32 v246, 0x2400, v246
	v_add_u32_e32 v246, v246, v240
	global_load_dwordx4 v[66:69], v246, s[8:9] offset:0
	global_load_dwordx4 v[70:73], v246, s[8:9] offset:32
	global_load_dwordx4 v[74:77], v246, s[8:9] offset:64
	global_load_dwordx4 v[78:81], v246, s[8:9] offset:96
	global_load_dwordx4 v[82:85], v232, s[8:9] offset:0
	global_load_dwordx4 v[86:89], v232, s[8:9] offset:32
	global_load_dwordx4 v[90:93], v232, s[8:9] offset:64
	global_load_dwordx4 v[94:97], v232, s[8:9] offset:96
	s_waitcnt vmcnt(24)
; DI void phase_attn_a(int wv_, int vb_, int nvb_, char* ws_, const Ctx& p, char* smem) {
;     ...
;   for (int k_ = 0; k_ < (6144 + nvb_ - 1) / nvb_; ++k_) {
;     const int u = (vb_ + k_ * nvb_ < 6144) ? vb_ + k_ * nvb_ : 6143;
;     const int head = u & 7, g = (u >> 3) % 3, rest = u / 24, idx = rest & 31, b = rest >> 5;
;     const int dil = (g == 0) ? 1 : ((g == 1) ? 4 : 16);
;     const int nbper = 32 / dil, r = idx / nbper, nb = idx % nbper;
;     u16* Og = (g == 0) ? (u16*)(ws_ + WS_H) : ((g == 1) ? (u16*)(ws_ + WS_H + 32 * MiB) : (u16*)(ws_ + WS_E));
;     float* lse = (float*)(ws_ + WS_LSE) + (size_t)g * NTOK * 8;
;     if (tid <= 128) sBias[tid] = p.rel_bias[t5_bucket(tid * dil) * 40 + g * 8 + head] * 1.4426950408889634f;
;     {
;       const int kk = tid; const int ksub = nb * 128 - 128 + kk;
;       bf16x8 v[8];
;       if (ksub >= 0) {
;         const u16* vp = P + ((size_t)b * SEQ + (size_t)ksub * dil + r) * 4608 + 3072 + g * 512 + head * 64;
; #pragma unroll
;         for (int i = 0; i < 8; ++i) v[i] = *(const bf16x8*)(vp + i * 8);
;       } else {
; #pragma unroll
;         for (int i = 0; i < 8; ++i) v[i] = zero8();
;       }
; #pragma unroll
;       for (int i = 0; i < 8; ++i)
; #pragma unroll
;         for (int jj = 0; jj < 8; ++jj) Vt[(i * 8 + jj) * 260 + kk] = (u16)v[i][jj];
;     }
;     __syncthreads();
	ds_write_b16 v223, v98
	ds_write_b16_d16_hi v223, v98 offset:520
	ds_write_b16 v223, v99 offset:1040
	ds_write_b16_d16_hi v223, v99 offset:1560
	ds_write_b16 v223, v100 offset:2080
	ds_write_b16_d16_hi v223, v100 offset:2600
	ds_write_b16 v223, v101 offset:3120
	ds_write_b16_d16_hi v223, v101 offset:3640
	ds_write_b16 v223, v102 offset:4160
	ds_write_b16_d16_hi v223, v102 offset:4680
	ds_write_b16 v223, v103 offset:5200
	ds_write_b16_d16_hi v223, v103 offset:5720
	ds_write_b16 v223, v104 offset:6240
	ds_write_b16_d16_hi v223, v104 offset:6760
	ds_write_b16 v223, v105 offset:7280
	ds_write_b16_d16_hi v223, v105 offset:7800
	ds_write_b16 v223, v106 offset:8320
	ds_write_b16_d16_hi v223, v106 offset:8840
	ds_write_b16 v223, v107 offset:9360
	ds_write_b16_d16_hi v223, v107 offset:9880
	ds_write_b16 v223, v108 offset:10400
	ds_write_b16_d16_hi v223, v108 offset:10920
	ds_write_b16 v223, v109 offset:11440
	ds_write_b16_d16_hi v223, v109 offset:11960
	ds_write_b16 v223, v110 offset:12480
	ds_write_b16_d16_hi v223, v110 offset:13000
	ds_write_b16 v223, v111 offset:13520
	ds_write_b16_d16_hi v223, v111 offset:14040
	ds_write_b16 v223, v112 offset:14560
	ds_write_b16_d16_hi v223, v112 offset:15080
	ds_write_b16 v223, v113 offset:15600
	ds_write_b16_d16_hi v223, v113 offset:16120
	ds_write_b16 v223, v114 offset:16640
	ds_write_b16_d16_hi v223, v114 offset:17160
	ds_write_b16 v223, v115 offset:17680
	ds_write_b16_d16_hi v223, v115 offset:18200
	ds_write_b16 v223, v116 offset:18720
	ds_write_b16_d16_hi v223, v116 offset:19240
	ds_write_b16 v223, v117 offset:19760
	ds_write_b16_d16_hi v223, v117 offset:20280
	ds_write_b16 v223, v118 offset:20800
	ds_write_b16_d16_hi v223, v118 offset:21320
	ds_write_b16 v223, v119 offset:21840
	ds_write_b16_d16_hi v223, v119 offset:22360
	ds_write_b16 v223, v120 offset:22880
	ds_write_b16_d16_hi v223, v120 offset:23400
	ds_write_b16 v223, v121 offset:23920
	ds_write_b16_d16_hi v223, v121 offset:24440
	ds_write_b16 v223, v122 offset:24960
	ds_write_b16_d16_hi v223, v122 offset:25480
	ds_write_b16 v223, v123 offset:26000
	ds_write_b16_d16_hi v223, v123 offset:26520
	ds_write_b16 v223, v124 offset:27040
	ds_write_b16_d16_hi v223, v124 offset:27560
	ds_write_b16 v223, v125 offset:28080
	ds_write_b16_d16_hi v223, v125 offset:28600
	ds_write_b16 v223, v126 offset:29120
	ds_write_b16_d16_hi v223, v126 offset:29640
	ds_write_b16 v223, v127 offset:30160
	ds_write_b16_d16_hi v223, v127 offset:30680
	ds_write_b16 v223, v128 offset:31200
	ds_write_b16_d16_hi v223, v128 offset:31720
	ds_write_b16 v223, v129 offset:32240
	ds_write_b16_d16_hi v223, v129 offset:32760
	v_mul_f32_e32 v196, 0x3fb8aa3b, v229
	v_cndmask_b32_e64 v196, v207, v196, s[66:67]
	ds_write_b32 v224, v196
	s_waitcnt lgkmcnt(0)
	s_barrier
	s_mov_b32 s2, s13
	s_mov_b64 s[4:5], s[14:15]
	s_mov_b64 s[6:7], s[18:19]
	v_mov_b32_e32 v225, v226
	v_mov_b32_e32 v227, v228
	v_add_u32_e32 v221, s64, v209
	v_add_u32_e32 v222, s65, v216
	s_sub_i32 s64, 0x8200, s64
	s_sub_i32 s65, 0x400, s65
	s_mov_b32 s34, 0
.Lattn_loop:
	s_add_i32 s0, s34, 1
	s_mul_i32 s0, s0, s45
	s_add_i32 s0, s0, s44
	s_min_i32 s0, s0, 0x17ff
	s_and_b32 s1, s0, 7
	s_lshr_b32 s3, s0, 3
	s_mul_hi_u32 s63, s3, 0xaaaaaaab
	s_lshr_b32 s63, s63, 1
	s_mul_i32 s68, s63, 3
	s_sub_i32 s62, s3, s68
	s_and_b32 s69, s63, 31
	s_lshr_b32 s70, s63, 5
	s_lshl_b32 s10, s62, 1
	s_sub_i32 s71, 5, s10
	s_lshr_b32 s11, s69, s71
	s_lshr_b32 s72, 32, s10
	s_add_i32 s72, s72, -1
	s_and_b32 s72, s69, s72
	s_lshl_b32 s12, s72, 7
	s_sub_i32 s73, 4, s60
	s_lshl_b32 s73, 1, s73
	s_add_i32 s73, s73, -1
	s_cmp_eq_u32 s72, 0
	s_cselect_b32 s13, s73, 0
	s_mul_i32 s73, s70, 0x2400000
	s_lshl_b32 s74, s62, 10
	s_lshl_b32 s75, s1, 7
	s_add_i32 s73, s73, s74
	s_add_i32 s73, s73, s75
	s_add_u32 s8, s86, s73
	s_addc_u32 s9, s87, 0
	s_mov_b32 s73, 0x8600000
	s_cmp_eq_u32 s62, 0
	s_cselect_b32 s73, 0x6600000, s73
	s_cmp_eq_u32 s62, 2
	s_cselect_b32 s73, 0x1c600000, s73
	s_lshl_b32 s74, s70, 22
	s_add_i32 s73, s73, s74
	s_add_i32 s73, s73, s75
	s_add_u32 s14, s78, s73
	s_addc_u32 s15, s79, 0
	s_lshl_b32 s73, s62, 20
	s_lshl_b32 s74, s70, 17
	s_add_i32 s73, s73, s74
	s_lshl_b32 s74, s1, 2
	s_add_i32 s73, s73, s74
	s_add_i32 s73, s73, 0x1e600000
	s_add_u32 s18, s78, s73
	s_addc_u32 s19, s79, 0
	s_lshl_b32 s61, s62, 3
	s_add_i32 s61, s61, s1
	s_lshl_b32 s61, s61, 2
	v_add_u32_e32 v231, s12, v200
	v_lshlrev_b32_e32 v196, s10, v231
	v_add_u32_e32 v196, s11, v196
	v_lshl_add_u32 v226, v196, 10, v239
	v_lshlrev_b32_e32 v228, 5, v196
	v_mul_u32_u24_e32 v196, 0x2400, v196
	v_add_u32_e32 v232, v196, v201
	v_add_u32_e32 v223, s64, v203
	v_add_u32_e32 v224, s65, v217
	s_cmp_eq_u32 s34, 0
	s_cbranch_scc1 .Lattn_w0
	s_waitcnt vmcnt(9)
	s_branch .Lattn_w1

; #define MFMA32(a, b, c) __builtin_amdgcn_mfma_f32_32x32x16_bf16((a), (b), (c), 0, 0, 0)
; DI int shx(int v, int m) { return __builtin_amdgcn_ds_bpermute((lane_now() ^ m) << 2, v); }
; DI void phase_attn_a(int wv_, int vb_, int nvb_, char* ws_, const Ctx& p, char* smem) {
;     ...
;       float mx = -INFINITY, sum = 0.f;
;       f32x16 oacc[2]; oacc[0] = zero16(); oacc[1] = zero16();
; #pragma unroll 1
;       for (int kb = 0; kb < 5; ++kb) {
;         const int kk = 32 * wave + 32 * kb + c; const int ksub0 = nb * 128 - 128 + kk;
;         bf16x8 kf[4];
;         if (ksub0 >= 0) {
;           const u16* kp = P + ((size_t)b * SEQ + (size_t)ksub0 * dil + r) * 4608 + 1536 + g * 512 + head * 64;
; #pragma unroll
;           for (int ks = 0; ks < 4; ++ks) kf[ks] = *(const bf16x8*)(kp + ks * 16 + h * 8);
;         } else {
; #pragma unroll
;           for (int ks = 0; ks < 4; ++ks) kf[ks] = zero8();
;         }
;         f32x16 sa = zero16();
; #pragma unroll
;         for (int ks = 0; ks < 4; ++ks) sa = MFMA32(kf[ks], qf[ks], sa);
;         float bm = -INFINITY;
;         const int sbase = c + 128 - 32 * kb - 4 * h;
;         const unsigned slim = (unsigned)((nb * 128 + 32 * wave + c) < 128 ? (nb * 128 + 32 * wave + c) : 128);
;         if (nb > 0 && kb >= 1 && kb <= 3) {
; #pragma unroll
;           for (int i = 0; i < 16; ++i) {
;             const int step = sbase - ((i & 3) + 8 * (i >> 2));
;             const float v = sa[i] + sBias[step];
;             sa[i] = v; bm = fmaxf(bm, v);
;           }
;         } else {
; #pragma unroll
;           for (int i = 0; i < 16; ++i) {
;             const int step = sbase - ((i & 3) + 8 * (i >> 2));
;             const bool valid = (unsigned)step <= slim;
;             const float bv = sBias[step];
;             float v = valid ? sa[i] + bv : -INFINITY;
;             sa[i] = v; bm = fmaxf(bm, v);
;           }
;         }
;         bm = fmaxf(bm, shx(bm, 32));
;         const float mnew = fmaxf(mx, bm);
;         const float mref = (mnew == -INFINITY) ? 0.f : mnew;
;         const float scale = __builtin_amdgcn_exp2f(mx - mref);
;         float ps = 0.f;
; #pragma unroll
;         for (int i = 0; i < 16; ++i) { float pv = __builtin_amdgcn_exp2f(sa[i] - mref); sa[i] = pv; ps += pv; }
;         sum = sum * scale + ps; mx = mnew;
; #pragma unroll
;         for (int i = 0; i < 16; ++i) { oacc[0][i] *= scale; oacc[1][i] *= scale; }
.Lattn_w1:
	v_add_u32_e32 v230, s12, v241
	v_max_i32_e32 v230, 0, v230
	v_lshlrev_b32_e32 v230, s10, v230
	v_add_u32_e32 v230, s11, v230
	v_mul_u32_u24_e32 v230, 0x2400, v230
	v_add_u32_e32 v230, 0x1800, v230
	global_load_dwordx4 v[98:101], v230, s[8:9] offset:0
	global_load_dwordx4 v[102:105], v230, s[8:9] offset:16
	global_load_dwordx4 v[106:109], v230, s[8:9] offset:32
	global_load_dwordx4 v[110:113], v230, s[8:9] offset:48
	global_load_dwordx4 v[114:117], v230, s[8:9] offset:64
	global_load_dwordx4 v[118:121], v230, s[8:9] offset:80
	global_load_dwordx4 v[122:125], v230, s[8:9] offset:96
	global_load_dwordx4 v[126:129], v230, s[8:9] offset:112
	s_cmp_eq_u32 s62, 0
	s_cselect_b64 vcc, -1, 0
	v_cndmask_b32_e32 v196, v219, v218, vcc
	s_cmp_eq_u32 s62, 2
	s_cselect_b64 vcc, -1, 0
	v_cndmask_b32_e32 v196, v196, v220, vcc
	v_add_u32_e32 v196, s61, v196
	global_load_dword v229, v196, s[56:57]
	v_mov_b32_e32 v194, v207
	v_mov_b32_e32 v195, 0
	v_mov_b32_e32 v146, 0
	v_mov_b32_e32 v147, 0
	v_mov_b32_e32 v148, 0
	v_mov_b32_e32 v149, 0
	v_mov_b32_e32 v150, 0
	v_mov_b32_e32 v151, 0
	v_mov_b32_e32 v152, 0
	v_mov_b32_e32 v153, 0
	v_mov_b32_e32 v154, 0
	v_mov_b32_e32 v155, 0
	v_mov_b32_e32 v156, 0
	v_mov_b32_e32 v157, 0
	v_mov_b32_e32 v158, 0
	v_mov_b32_e32 v159, 0
	v_mov_b32_e32 v160, 0
	v_mov_b32_e32 v161, 0
	v_mov_b32_e32 v162, 0
	v_mov_b32_e32 v163, 0
	v_mov_b32_e32 v164, 0
	v_mov_b32_e32 v165, 0
	v_mov_b32_e32 v166, 0
	v_mov_b32_e32 v167, 0
	v_mov_b32_e32 v168, 0
	v_mov_b32_e32 v169, 0
	v_mov_b32_e32 v170, 0
	v_mov_b32_e32 v171, 0
	v_mov_b32_e32 v172, 0
	v_mov_b32_e32 v173, 0
	v_mov_b32_e32 v174, 0
	v_mov_b32_e32 v175, 0
	v_mov_b32_e32 v176, 0
	v_mov_b32_e32 v177, 0
	s_bitcmp1_b32 s2, 0
	s_cbranch_scc1 .Lattn_skip0
	v_mfma_f32_32x32x16_bf16 v[130:145], v[2:5], v[82:85], 0
	v_mfma_f32_32x32x16_bf16 v[130:145], v[6:9], v[86:89], v[130:145]
	v_mfma_f32_32x32x16_bf16 v[130:145], v[10:13], v[90:93], v[130:145]
	v_mfma_f32_32x32x16_bf16 v[130:145], v[14:17], v[94:97], v[130:145]
	v_add_u32_e32 v246, 0xffffff80, v231
	v_max_i32_e32 v246, 0, v246
	v_lshlrev_b32_e32 v246, s10, v246
	v_add_u32_e32 v246, s11, v246
	v_mul_u32_u24_e32 v246, 0x2400, v246
	v_add_u32_e32 v246, v246, v240
	global_load_dwordx4 v[2:5], v246, s[8:9] offset:0
	global_load_dwordx4 v[6:9], v246, s[8:9] offset:32
	global_load_dwordx4 v[10:13], v246, s[8:9] offset:64
	global_load_dwordx4 v[14:17], v246, s[8:9] offset:96
	ds_read2_b32 v[178:179], v222 offset0:159 offset1:158
	ds_read2_b32 v[180:181], v222 offset0:157 offset1:156
	ds_read2_b32 v[182:183], v222 offset0:151 offset1:150
	ds_read2_b32 v[184:185], v222 offset0:149 offset1:148
	ds_read2_b32 v[186:187], v222 offset0:143 offset1:142
	ds_read2_b32 v[188:189], v222 offset0:141 offset1:140
	ds_read2_b32 v[190:191], v222 offset0:135 offset1:134
	ds_read2_b32 v[192:193], v222 offset0:133 offset1:132
	s_waitcnt lgkmcnt(0)
	v_add_f32_e32 v130, v130, v178
	v_add_f32_e32 v131, v131, v179
	v_add_f32_e32 v132, v132, v180
	v_add_f32_e32 v133, v133, v181
	v_add_f32_e32 v134, v134, v182
	v_add_f32_e32 v135, v135, v183
	v_add_f32_e32 v136, v136, v184
	v_add_f32_e32 v137, v137, v185
	v_add_f32_e32 v138, v138, v186
	v_add_f32_e32 v139, v139, v187
	v_add_f32_e32 v140, v140, v188
	v_add_f32_e32 v141, v141, v189
	v_add_f32_e32 v142, v142, v190
	v_add_f32_e32 v143, v143, v191
	v_add_f32_e32 v144, v144, v192
	v_add_f32_e32 v145, v145, v193
	ds_read_b64 v[178:179], v221
	ds_read_b64 v[180:181], v221 offset:16
	ds_read_b64 v[182:183], v221 offset:16640
	ds_read_b64 v[184:185], v221 offset:16656
	ds_read_b64 v[186:187], v221 offset:32
	ds_read_b64 v[188:189], v221 offset:48
	ds_read_b64 v[190:191], v221 offset:16672
	ds_read_b64 v[192:193], v221 offset:16688
	v_max3_f32 v235, v130, v131, v132
	v_max3_f32 v235, v235, v133, v134
	v_max3_f32 v235, v235, v135, v136
	v_max3_f32 v235, v235, v137, v138
	v_max3_f32 v235, v235, v139, v140
	v_max3_f32 v235, v235, v141, v142
	v_max3_f32 v235, v235, v143, v144
	v_max_f32_e32 v235, v235, v145
	v_mov_b32_e32 v196, v235
	s_nop 1
	v_permlane32_swap_b32_e32 v196, v235
	v_max_f32_e32 v235, v235, v196
	v_max_f32_e32 v234, v194, v235
	v_cmp_eq_f32_e32 vcc, 0xff800000, v234
	s_nop 1
	v_cndmask_b32_e64 v237, v234, 0, vcc
	v_sub_f32_e32 v196, v194, v237
	v_exp_f32_e32 v233, v196
	v_sub_f32_e32 v130, v130, v237
	v_sub_f32_e32 v131, v131, v237
	v_sub_f32_e32 v132, v132, v237
	v_sub_f32_e32 v133, v133, v237
	v_sub_f32_e32 v134, v134, v237
	v_sub_f32_e32 v135, v135, v237
	v_sub_f32_e32 v136, v136, v237
	v_sub_f32_e32 v137, v137, v237
	v_sub_f32_e32 v138, v138, v237
	v_sub_f32_e32 v139, v139, v237
	v_sub_f32_e32 v140, v140, v237
	v_sub_f32_e32 v141, v141, v237
	v_sub_f32_e32 v142, v142, v237
	v_sub_f32_e32 v143, v143, v237
	v_sub_f32_e32 v144, v144, v237
	v_sub_f32_e32 v145, v145, v237
	v_exp_f32_e32 v130, v130
	v_exp_f32_e32 v131, v131
	v_exp_f32_e32 v132, v132
	v_exp_f32_e32 v133, v133
	v_exp_f32_e32 v134, v134
	v_exp_f32_e32 v135, v135
	v_exp_f32_e32 v136, v136
	v_exp_f32_e32 v137, v137
	v_exp_f32_e32 v138, v138
	v_exp_f32_e32 v139, v139
	v_exp_f32_e32 v140, v140
	v_exp_f32_e32 v141, v141
	v_exp_f32_e32 v142, v142
	v_exp_f32_e32 v143, v143
	v_exp_f32_e32 v144, v144
	v_exp_f32_e32 v145, v145
	v_mov_b32_e32 v194, v234
	v_add_f32_e32 v236, v130, v131
	v_add_f32_e32 v236, v236, v132
	v_add_f32_e32 v236, v236, v133
	v_add_f32_e32 v236, v236, v134
	v_add_f32_e32 v236, v236, v135
	v_add_f32_e32 v236, v236, v136
	v_add_f32_e32 v236, v236, v137
	v_add_f32_e32 v236, v236, v138
	v_add_f32_e32 v236, v236, v139
	v_add_f32_e32 v236, v236, v140
	v_add_f32_e32 v236, v236, v141
	v_add_f32_e32 v236, v236, v142
	v_add_f32_e32 v236, v236, v143
; DI void phase_attn_a(int wv_, int vb_, int nvb_, char* ws_, const Ctx& p, char* smem) {
;     ...
;       for (int kb = 0; kb < 5; ++kb) {
;         const int kk = 32 * wave + 32 * kb + c; const int ksub0 = nb * 128 - 128 + kk;
;         bf16x8 kf[4];
;         if (ksub0 >= 0) {
;           const u16* kp = P + ((size_t)b * SEQ + (size_t)ksub0 * dil + r) * 4608 + 1536 + g * 512 + head * 64;
; #pragma unroll
;           for (int ks = 0; ks < 4; ++ks) kf[ks] = *(const bf16x8*)(kp + ks * 16 + h * 8);
;         } else {
; #pragma unroll
;           for (int ks = 0; ks < 4; ++ks) kf[ks] = zero8();
;         }
;         f32x16 sa = zero16();
; #pragma unroll
;         for (int ks = 0; ks < 4; ++ks) sa = MFMA32(kf[ks], qf[ks], sa);
;         float bm = -INFINITY;
;         const int sbase = c + 128 - 32 * kb - 4 * h;
;         const unsigned slim = (unsigned)((nb * 128 + 32 * wave + c) < 128 ? (nb * 128 + 32 * wave + c) : 128);
;         if (nb > 0 && kb >= 1 && kb <= 3) {
; #pragma unroll
;           for (int i = 0; i < 16; ++i) {
;             const int step = sbase - ((i & 3) + 8 * (i >> 2));
;             const float v = sa[i] + sBias[step];
;             sa[i] = v; bm = fmaxf(bm, v);
;           }
;         } else {
; #pragma unroll
;           for (int i = 0; i < 16; ++i) {
;             const int step = sbase - ((i & 3) + 8 * (i >> 2));
;             const bool valid = (unsigned)step <= slim;
;             const float bv = sBias[step];
;             float v = valid ? sa[i] + bv : -INFINITY;
;             sa[i] = v; bm = fmaxf(bm, v);
;           }
;         }
;         bm = fmaxf(bm, shx(bm, 32));
;         const float mnew = fmaxf(mx, bm);
;         const float mref = (mnew == -INFINITY) ? 0.f : mnew;
;         const float scale = __builtin_amdgcn_exp2f(mx - mref);
;         float ps = 0.f;
; #pragma unroll
;         for (int i = 0; i < 16; ++i) { float pv = __builtin_amdgcn_exp2f(sa[i] - mref); sa[i] = pv; ps += pv; }
;         sum = sum * scale + ps; mx = mnew;
; #pragma unroll
;         for (int i = 0; i < 16; ++i) { oacc[0][i] *= scale; oacc[1][i] *= scale; }
; #pragma unroll
;         for (int s = 0; s < 2; ++s) {
;           bf16x8 pb = pack8(sa, s);
;           const int keybase = 32 * wave + 32 * kb + 16 * s;
; #pragma unroll
;           for (int mb = 0; mb < 2; ++mb) {
;             const u16* vr = Vt + (mb * 32 + c) * 260 + keybase + 4 * h;
	v_add_f32_e32 v236, v236, v144
	v_add_f32_e32 v236, v236, v145
	v_fma_f32 v195, v195, v233, v236
	v_mul_f32_e32 v146, v233, v146
	v_mul_f32_e32 v147, v233, v147
	v_mul_f32_e32 v148, v233, v148
	v_mul_f32_e32 v149, v233, v149
	v_mul_f32_e32 v150, v233, v150
	v_mul_f32_e32 v151, v233, v151
	v_mul_f32_e32 v152, v233, v152
	v_mul_f32_e32 v153, v233, v153
	v_mul_f32_e32 v154, v233, v154
	v_mul_f32_e32 v155, v233, v155
	v_mul_f32_e32 v156, v233, v156
	v_mul_f32_e32 v157, v233, v157
	v_mul_f32_e32 v158, v233, v158
	v_mul_f32_e32 v159, v233, v159
	v_mul_f32_e32 v160, v233, v160
	v_mul_f32_e32 v161, v233, v161
	v_mul_f32_e32 v162, v233, v162
	v_mul_f32_e32 v163, v233, v163
	v_mul_f32_e32 v164, v233, v164
	v_mul_f32_e32 v165, v233, v165
	v_mul_f32_e32 v166, v233, v166
	v_mul_f32_e32 v167, v233, v167
	v_mul_f32_e32 v168, v233, v168
	v_mul_f32_e32 v169, v233, v169
	v_mul_f32_e32 v170, v233, v170
	v_mul_f32_e32 v171, v233, v171
	v_mul_f32_e32 v172, v233, v172
	v_mul_f32_e32 v173, v233, v173
	v_mul_f32_e32 v174, v233, v174
	v_mul_f32_e32 v175, v233, v175
	v_mul_f32_e32 v176, v233, v176
	v_mul_f32_e32 v177, v233, v177
	v_cvt_pk_bf16_f32 v130, v130, v131
	v_cvt_pk_bf16_f32 v131, v132, v133
	v_cvt_pk_bf16_f32 v132, v134, v135
	v_cvt_pk_bf16_f32 v133, v136, v137
	v_cvt_pk_bf16_f32 v134, v138, v139
	v_cvt_pk_bf16_f32 v135, v140, v141
	v_cvt_pk_bf16_f32 v136, v142, v143
	v_cvt_pk_bf16_f32 v137, v144, v145
	s_waitcnt lgkmcnt(0)
	s_nop 1
	v_mfma_f32_32x32x16_bf16 v[146:161], v[178:181], v[130:133], v[146:161]
	v_mfma_f32_32x32x16_bf16 v[162:177], v[182:185], v[130:133], v[162:177]
	v_mfma_f32_32x32x16_bf16 v[146:161], v[186:189], v[134:137], v[146:161]
	v_mfma_f32_32x32x16_bf16 v[162:177], v[190:193], v[134:137], v[162:177]
	s_branch .Lattn_end0
.Lattn_skip0:
	v_add_u32_e32 v246, 0xffffff80, v231
	v_max_i32_e32 v246, 0, v246
	v_lshlrev_b32_e32 v246, s10, v246
	v_add_u32_e32 v246, s11, v246
	v_mul_u32_u24_e32 v246, 0x2400, v246
	v_add_u32_e32 v246, v246, v240
	global_load_dwordx4 v[2:5], v246, s[8:9] offset:0
	global_load_dwordx4 v[6:9], v246, s[8:9] offset:32
	global_load_dwordx4 v[10:13], v246, s[8:9] offset:64
	global_load_dwordx4 v[14:17], v246, s[8:9] offset:96
.Lattn_end0:
	s_bitcmp1_b32 s2, 1
	s_cbranch_scc1 .Lattn_skip1
	v_mfma_f32_32x32x16_bf16 v[130:145], v[18:21], v[82:85], 0
	v_mfma_f32_32x32x16_bf16 v[130:145], v[22:25], v[86:89], v[130:145]
	v_mfma_f32_32x32x16_bf16 v[130:145], v[26:29], v[90:93], v[130:145]
	v_mfma_f32_32x32x16_bf16 v[130:145], v[30:33], v[94:97], v[130:145]
	v_add_u32_e32 v246, 0xffffffa0, v231
	v_max_i32_e32 v246, 0, v246
	v_lshlrev_b32_e32 v246, s10, v246
	v_add_u32_e32 v246, s11, v246
	v_mul_u32_u24_e32 v246, 0x2400, v246
	v_add_u32_e32 v246, v246, v240
	global_load_dwordx4 v[18:21], v246, s[8:9] offset:0
	global_load_dwordx4 v[22:25], v246, s[8:9] offset:32
	global_load_dwordx4 v[26:29], v246, s[8:9] offset:64
	global_load_dwordx4 v[30:33], v246, s[8:9] offset:96
	ds_read2_b32 v[178:179], v222 offset0:127 offset1:126
	ds_read2_b32 v[180:181], v222 offset0:125 offset1:124
	ds_read2_b32 v[182:183], v222 offset0:119 offset1:118
	ds_read2_b32 v[184:185], v222 offset0:117 offset1:116
	ds_read2_b32 v[186:187], v222 offset0:111 offset1:110
	ds_read2_b32 v[188:189], v222 offset0:109 offset1:108
	ds_read2_b32 v[190:191], v222 offset0:103 offset1:102
	ds_read2_b32 v[192:193], v222 offset0:101 offset1:100
	s_waitcnt lgkmcnt(0)
	v_add_f32_e32 v130, v130, v178
	v_add_f32_e32 v131, v131, v179
	v_add_f32_e32 v132, v132, v180
	v_add_f32_e32 v133, v133, v181
	v_add_f32_e32 v134, v134, v182
	v_add_f32_e32 v135, v135, v183
	v_add_f32_e32 v136, v136, v184
	v_add_f32_e32 v137, v137, v185
	v_add_f32_e32 v138, v138, v186
	v_add_f32_e32 v139, v139, v187
	v_add_f32_e32 v140, v140, v188
	v_add_f32_e32 v141, v141, v189
	v_add_f32_e32 v142, v142, v190
	v_add_f32_e32 v143, v143, v191
	v_add_f32_e32 v144, v144, v192
	v_add_f32_e32 v145, v145, v193
	ds_read_b64 v[178:179], v221 offset:64
	ds_read_b64 v[180:181], v221 offset:80
	ds_read_b64 v[182:183], v221 offset:16704
	ds_read_b64 v[184:185], v221 offset:16720
	ds_read_b64 v[186:187], v221 offset:96
	ds_read_b64 v[188:189], v221 offset:112
	ds_read_b64 v[190:191], v221 offset:16736
	ds_read_b64 v[192:193], v221 offset:16752
	v_max3_f32 v235, v130, v131, v132
	v_max3_f32 v235, v235, v133, v134
	v_max3_f32 v235, v235, v135, v136
	v_max3_f32 v235, v235, v137, v138
	v_max3_f32 v235, v235, v139, v140
	v_max3_f32 v235, v235, v141, v142
	v_max3_f32 v235, v235, v143, v144
	v_max_f32_e32 v235, v235, v145
	v_mov_b32_e32 v196, v235
	s_nop 1
	v_permlane32_swap_b32_e32 v196, v235
	v_max_f32_e32 v235, v235, v196
	v_max_f32_e32 v234, v194, v235
	v_cmp_eq_f32_e32 vcc, 0xff800000, v234
	s_nop 1
	v_cndmask_b32_e64 v237, v234, 0, vcc
	v_sub_f32_e32 v196, v194, v237
	v_exp_f32_e32 v233, v196
	v_sub_f32_e32 v130, v130, v237
	v_sub_f32_e32 v131, v131, v237
	v_sub_f32_e32 v132, v132, v237
	v_sub_f32_e32 v133, v133, v237
	v_sub_f32_e32 v134, v134, v237
	v_sub_f32_e32 v135, v135, v237
	v_sub_f32_e32 v136, v136, v237
	v_sub_f32_e32 v137, v137, v237
	v_sub_f32_e32 v138, v138, v237
	v_sub_f32_e32 v139, v139, v237
	v_sub_f32_e32 v140, v140, v237
	v_sub_f32_e32 v141, v141, v237
	v_sub_f32_e32 v142, v142, v237
	v_sub_f32_e32 v143, v143, v237
	v_sub_f32_e32 v144, v144, v237
	v_sub_f32_e32 v145, v145, v237
	v_exp_f32_e32 v130, v130
	v_exp_f32_e32 v131, v131
	v_exp_f32_e32 v132, v132
	v_exp_f32_e32 v133, v133
	v_exp_f32_e32 v134, v134
	v_exp_f32_e32 v135, v135
	v_exp_f32_e32 v136, v136
	v_exp_f32_e32 v137, v137
	v_exp_f32_e32 v138, v138
	v_exp_f32_e32 v139, v139
	v_exp_f32_e32 v140, v140
	v_exp_f32_e32 v141, v141
	v_exp_f32_e32 v142, v142
; DI void phase_attn_a(int wv_, int vb_, int nvb_, char* ws_, const Ctx& p, char* smem) {
;     ...
;       for (int kb = 0; kb < 5; ++kb) {
;         const int kk = 32 * wave + 32 * kb + c; const int ksub0 = nb * 128 - 128 + kk;
;         bf16x8 kf[4];
;         if (ksub0 >= 0) {
;           const u16* kp = P + ((size_t)b * SEQ + (size_t)ksub0 * dil + r) * 4608 + 1536 + g * 512 + head * 64;
; #pragma unroll
;           for (int ks = 0; ks < 4; ++ks) kf[ks] = *(const bf16x8*)(kp + ks * 16 + h * 8);
;         } else {
; #pragma unroll
;           for (int ks = 0; ks < 4; ++ks) kf[ks] = zero8();
;         }
;         f32x16 sa = zero16();
; #pragma unroll
;         for (int ks = 0; ks < 4; ++ks) sa = MFMA32(kf[ks], qf[ks], sa);
;         float bm = -INFINITY;
;         const int sbase = c + 128 - 32 * kb - 4 * h;
;         const unsigned slim = (unsigned)((nb * 128 + 32 * wave + c) < 128 ? (nb * 128 + 32 * wave + c) : 128);
;         if (nb > 0 && kb >= 1 && kb <= 3) {
; #pragma unroll
;           for (int i = 0; i < 16; ++i) {
;             const int step = sbase - ((i & 3) + 8 * (i >> 2));
;             const float v = sa[i] + sBias[step];
;             sa[i] = v; bm = fmaxf(bm, v);
;           }
;         } else {
; #pragma unroll
;           for (int i = 0; i < 16; ++i) {
;             const int step = sbase - ((i & 3) + 8 * (i >> 2));
;             const bool valid = (unsigned)step <= slim;
;             const float bv = sBias[step];
;             float v = valid ? sa[i] + bv : -INFINITY;
;             sa[i] = v; bm = fmaxf(bm, v);
;           }
;         }
;         bm = fmaxf(bm, shx(bm, 32));
;         const float mnew = fmaxf(mx, bm);
;         const float mref = (mnew == -INFINITY) ? 0.f : mnew;
;         const float scale = __builtin_amdgcn_exp2f(mx - mref);
;         float ps = 0.f;
; #pragma unroll
;         for (int i = 0; i < 16; ++i) { float pv = __builtin_amdgcn_exp2f(sa[i] - mref); sa[i] = pv; ps += pv; }
;         sum = sum * scale + ps; mx = mnew;
; #pragma unroll
;         for (int i = 0; i < 16; ++i) { oacc[0][i] *= scale; oacc[1][i] *= scale; }
; #pragma unroll
;         for (int s = 0; s < 2; ++s) {
;           bf16x8 pb = pack8(sa, s);
;           const int keybase = 32 * wave + 32 * kb + 16 * s;
; #pragma unroll
;           for (int mb = 0; mb < 2; ++mb) {
;             const u16* vr = Vt + (mb * 32 + c) * 260 + keybase + 4 * h;
	v_exp_f32_e32 v143, v143
	v_exp_f32_e32 v144, v144
	v_exp_f32_e32 v145, v145
	v_mov_b32_e32 v194, v234
	v_add_f32_e32 v236, v130, v131
	v_add_f32_e32 v236, v236, v132
	v_add_f32_e32 v236, v236, v133
	v_add_f32_e32 v236, v236, v134
	v_add_f32_e32 v236, v236, v135
	v_add_f32_e32 v236, v236, v136
	v_add_f32_e32 v236, v236, v137
	v_add_f32_e32 v236, v236, v138
	v_add_f32_e32 v236, v236, v139
	v_add_f32_e32 v236, v236, v140
	v_add_f32_e32 v236, v236, v141
	v_add_f32_e32 v236, v236, v142
	v_add_f32_e32 v236, v236, v143
	v_add_f32_e32 v236, v236, v144
	v_add_f32_e32 v236, v236, v145
	v_fma_f32 v195, v195, v233, v236
	v_mul_f32_e32 v146, v233, v146
	v_mul_f32_e32 v147, v233, v147
	v_mul_f32_e32 v148, v233, v148
	v_mul_f32_e32 v149, v233, v149
	v_mul_f32_e32 v150, v233, v150
	v_mul_f32_e32 v151, v233, v151
	v_mul_f32_e32 v152, v233, v152
	v_mul_f32_e32 v153, v233, v153
	v_mul_f32_e32 v154, v233, v154
	v_mul_f32_e32 v155, v233, v155
	v_mul_f32_e32 v156, v233, v156
	v_mul_f32_e32 v157, v233, v157
	v_mul_f32_e32 v158, v233, v158
	v_mul_f32_e32 v159, v233, v159
	v_mul_f32_e32 v160, v233, v160
	v_mul_f32_e32 v161, v233, v161
	v_mul_f32_e32 v162, v233, v162
	v_mul_f32_e32 v163, v233, v163
	v_mul_f32_e32 v164, v233, v164
	v_mul_f32_e32 v165, v233, v165
	v_mul_f32_e32 v166, v233, v166
	v_mul_f32_e32 v167, v233, v167
	v_mul_f32_e32 v168, v233, v168
	v_mul_f32_e32 v169, v233, v169
	v_mul_f32_e32 v170, v233, v170
	v_mul_f32_e32 v171, v233, v171
	v_mul_f32_e32 v172, v233, v172
	v_mul_f32_e32 v173, v233, v173
	v_mul_f32_e32 v174, v233, v174
	v_mul_f32_e32 v175, v233, v175
	v_mul_f32_e32 v176, v233, v176
	v_mul_f32_e32 v177, v233, v177
	v_cvt_pk_bf16_f32 v130, v130, v131
	v_cvt_pk_bf16_f32 v131, v132, v133
	v_cvt_pk_bf16_f32 v132, v134, v135
	v_cvt_pk_bf16_f32 v133, v136, v137
	v_cvt_pk_bf16_f32 v134, v138, v139
	v_cvt_pk_bf16_f32 v135, v140, v141
	v_cvt_pk_bf16_f32 v136, v142, v143
	v_cvt_pk_bf16_f32 v137, v144, v145
	s_waitcnt lgkmcnt(0)
	s_nop 1
	v_mfma_f32_32x32x16_bf16 v[146:161], v[178:181], v[130:133], v[146:161]
	v_mfma_f32_32x32x16_bf16 v[162:177], v[182:185], v[130:133], v[162:177]
	v_mfma_f32_32x32x16_bf16 v[146:161], v[186:189], v[134:137], v[146:161]
	v_mfma_f32_32x32x16_bf16 v[162:177], v[190:193], v[134:137], v[162:177]
	s_branch .Lattn_end1
.Lattn_skip1:
	v_add_u32_e32 v246, 0xffffffa0, v231
	v_max_i32_e32 v246, 0, v246
	v_lshlrev_b32_e32 v246, s10, v246
	v_add_u32_e32 v246, s11, v246
	v_mul_u32_u24_e32 v246, 0x2400, v246
	v_add_u32_e32 v246, v246, v240
	global_load_dwordx4 v[18:21], v246, s[8:9] offset:0
	global_load_dwordx4 v[22:25], v246, s[8:9] offset:32
	global_load_dwordx4 v[26:29], v246, s[8:9] offset:64
	global_load_dwordx4 v[30:33], v246, s[8:9] offset:96
.Lattn_end1:
	s_bitcmp1_b32 s2, 2
	s_cbranch_scc1 .Lattn_skip2
	v_mfma_f32_32x32x16_bf16 v[130:145], v[34:37], v[82:85], 0
	v_mfma_f32_32x32x16_bf16 v[130:145], v[38:41], v[86:89], v[130:145]
	v_mfma_f32_32x32x16_bf16 v[130:145], v[42:45], v[90:93], v[130:145]
	v_mfma_f32_32x32x16_bf16 v[130:145], v[46:49], v[94:97], v[130:145]
	v_add_u32_e32 v246, 0xffffffc0, v231
	v_max_i32_e32 v246, 0, v246
	v_lshlrev_b32_e32 v246, s10, v246
	v_add_u32_e32 v246, s11, v246
	v_mul_u32_u24_e32 v246, 0x2400, v246
	v_add_u32_e32 v246, v246, v240
	global_load_dwordx4 v[34:37], v246, s[8:9] offset:0
	global_load_dwordx4 v[38:41], v246, s[8:9] offset:32
	global_load_dwordx4 v[42:45], v246, s[8:9] offset:64
	global_load_dwordx4 v[46:49], v246, s[8:9] offset:96
	ds_read2_b32 v[178:179], v222 offset0:95 offset1:94
	ds_read2_b32 v[180:181], v222 offset0:93 offset1:92
	ds_read2_b32 v[182:183], v222 offset0:87 offset1:86
	ds_read2_b32 v[184:185], v222 offset0:85 offset1:84
	ds_read2_b32 v[186:187], v222 offset0:79 offset1:78
	ds_read2_b32 v[188:189], v222 offset0:77 offset1:76
	ds_read2_b32 v[190:191], v222 offset0:71 offset1:70
	ds_read2_b32 v[192:193], v222 offset0:69 offset1:68
	s_waitcnt lgkmcnt(0)
	v_add_f32_e32 v130, v130, v178
	v_add_f32_e32 v131, v131, v179
	v_add_f32_e32 v132, v132, v180
	v_add_f32_e32 v133, v133, v181
	v_add_f32_e32 v134, v134, v182
	v_add_f32_e32 v135, v135, v183
	v_add_f32_e32 v136, v136, v184
	v_add_f32_e32 v137, v137, v185
	v_add_f32_e32 v138, v138, v186
	v_add_f32_e32 v139, v139, v187
	v_add_f32_e32 v140, v140, v188
	v_add_f32_e32 v141, v141, v189
	v_add_f32_e32 v142, v142, v190
	v_add_f32_e32 v143, v143, v191
	v_add_f32_e32 v144, v144, v192
	v_add_f32_e32 v145, v145, v193
	ds_read_b64 v[178:179], v221 offset:128
	ds_read_b64 v[180:181], v221 offset:144
	ds_read_b64 v[182:183], v221 offset:16768
	ds_read_b64 v[184:185], v221 offset:16784
	ds_read_b64 v[186:187], v221 offset:160
	ds_read_b64 v[188:189], v221 offset:176
	ds_read_b64 v[190:191], v221 offset:16800
	ds_read_b64 v[192:193], v221 offset:16816
	v_max3_f32 v235, v130, v131, v132
	v_max3_f32 v235, v235, v133, v134
	v_max3_f32 v235, v235, v135, v136
	v_max3_f32 v235, v235, v137, v138
	v_max3_f32 v235, v235, v139, v140
	v_max3_f32 v235, v235, v141, v142
	v_max3_f32 v235, v235, v143, v144
	v_max_f32_e32 v235, v235, v145
	v_mov_b32_e32 v196, v235
	s_nop 1
	v_permlane32_swap_b32_e32 v196, v235
	v_max_f32_e32 v235, v235, v196
	v_max_f32_e32 v234, v194, v235
	v_cmp_eq_f32_e32 vcc, 0xff800000, v234
	s_nop 1
	v_cndmask_b32_e64 v237, v234, 0, vcc
	v_sub_f32_e32 v196, v194, v237
	v_exp_f32_e32 v233, v196
	v_sub_f32_e32 v130, v130, v237
	v_sub_f32_e32 v131, v131, v237
	v_sub_f32_e32 v132, v132, v237
	v_sub_f32_e32 v133, v133, v237
	v_sub_f32_e32 v134, v134, v237
	v_sub_f32_e32 v135, v135, v237
	v_sub_f32_e32 v136, v136, v237
	v_sub_f32_e32 v137, v137, v237
	v_sub_f32_e32 v138, v138, v237
	v_sub_f32_e32 v139, v139, v237
; DI void phase_attn_a(int wv_, int vb_, int nvb_, char* ws_, const Ctx& p, char* smem) {
;     ...
;       for (int kb = 0; kb < 5; ++kb) {
;         const int kk = 32 * wave + 32 * kb + c; const int ksub0 = nb * 128 - 128 + kk;
;         bf16x8 kf[4];
;         if (ksub0 >= 0) {
;           const u16* kp = P + ((size_t)b * SEQ + (size_t)ksub0 * dil + r) * 4608 + 1536 + g * 512 + head * 64;
; #pragma unroll
;           for (int ks = 0; ks < 4; ++ks) kf[ks] = *(const bf16x8*)(kp + ks * 16 + h * 8);
;         } else {
; #pragma unroll
;           for (int ks = 0; ks < 4; ++ks) kf[ks] = zero8();
;         }
;         f32x16 sa = zero16();
; #pragma unroll
;         for (int ks = 0; ks < 4; ++ks) sa = MFMA32(kf[ks], qf[ks], sa);
;         float bm = -INFINITY;
;         const int sbase = c + 128 - 32 * kb - 4 * h;
;         const unsigned slim = (unsigned)((nb * 128 + 32 * wave + c) < 128 ? (nb * 128 + 32 * wave + c) : 128);
;         if (nb > 0 && kb >= 1 && kb <= 3) {
; #pragma unroll
;           for (int i = 0; i < 16; ++i) {
;             const int step = sbase - ((i & 3) + 8 * (i >> 2));
;             const float v = sa[i] + sBias[step];
;             sa[i] = v; bm = fmaxf(bm, v);
;           }
;         } else {
; #pragma unroll
;           for (int i = 0; i < 16; ++i) {
;             const int step = sbase - ((i & 3) + 8 * (i >> 2));
;             const bool valid = (unsigned)step <= slim;
;             const float bv = sBias[step];
;             float v = valid ? sa[i] + bv : -INFINITY;
;             sa[i] = v; bm = fmaxf(bm, v);
;           }
;         }
;         bm = fmaxf(bm, shx(bm, 32));
;         const float mnew = fmaxf(mx, bm);
;         const float mref = (mnew == -INFINITY) ? 0.f : mnew;
;         const float scale = __builtin_amdgcn_exp2f(mx - mref);
;         float ps = 0.f;
; #pragma unroll
;         for (int i = 0; i < 16; ++i) { float pv = __builtin_amdgcn_exp2f(sa[i] - mref); sa[i] = pv; ps += pv; }
;         sum = sum * scale + ps; mx = mnew;
; #pragma unroll
;         for (int i = 0; i < 16; ++i) { oacc[0][i] *= scale; oacc[1][i] *= scale; }
; #pragma unroll
;         for (int s = 0; s < 2; ++s) {
;           bf16x8 pb = pack8(sa, s);
;           const int keybase = 32 * wave + 32 * kb + 16 * s;
; #pragma unroll
;           for (int mb = 0; mb < 2; ++mb) {
;             const u16* vr = Vt + (mb * 32 + c) * 260 + keybase + 4 * h;
	v_sub_f32_e32 v140, v140, v237
	v_sub_f32_e32 v141, v141, v237
	v_sub_f32_e32 v142, v142, v237
	v_sub_f32_e32 v143, v143, v237
	v_sub_f32_e32 v144, v144, v237
	v_sub_f32_e32 v145, v145, v237
	v_exp_f32_e32 v130, v130
	v_exp_f32_e32 v131, v131
	v_exp_f32_e32 v132, v132
	v_exp_f32_e32 v133, v133
	v_exp_f32_e32 v134, v134
	v_exp_f32_e32 v135, v135
	v_exp_f32_e32 v136, v136
	v_exp_f32_e32 v137, v137
	v_exp_f32_e32 v138, v138
	v_exp_f32_e32 v139, v139
	v_exp_f32_e32 v140, v140
	v_exp_f32_e32 v141, v141
	v_exp_f32_e32 v142, v142
	v_exp_f32_e32 v143, v143
	v_exp_f32_e32 v144, v144
	v_exp_f32_e32 v145, v145
	v_mov_b32_e32 v194, v234
	v_add_f32_e32 v236, v130, v131
	v_add_f32_e32 v236, v236, v132
	v_add_f32_e32 v236, v236, v133
	v_add_f32_e32 v236, v236, v134
	v_add_f32_e32 v236, v236, v135
	v_add_f32_e32 v236, v236, v136
	v_add_f32_e32 v236, v236, v137
	v_add_f32_e32 v236, v236, v138
	v_add_f32_e32 v236, v236, v139
	v_add_f32_e32 v236, v236, v140
	v_add_f32_e32 v236, v236, v141
	v_add_f32_e32 v236, v236, v142
	v_add_f32_e32 v236, v236, v143
	v_add_f32_e32 v236, v236, v144
	v_add_f32_e32 v236, v236, v145
	v_fma_f32 v195, v195, v233, v236
	v_mul_f32_e32 v146, v233, v146
	v_mul_f32_e32 v147, v233, v147
	v_mul_f32_e32 v148, v233, v148
	v_mul_f32_e32 v149, v233, v149
	v_mul_f32_e32 v150, v233, v150
	v_mul_f32_e32 v151, v233, v151
	v_mul_f32_e32 v152, v233, v152
	v_mul_f32_e32 v153, v233, v153
	v_mul_f32_e32 v154, v233, v154
	v_mul_f32_e32 v155, v233, v155
	v_mul_f32_e32 v156, v233, v156
	v_mul_f32_e32 v157, v233, v157
	v_mul_f32_e32 v158, v233, v158
	v_mul_f32_e32 v159, v233, v159
	v_mul_f32_e32 v160, v233, v160
	v_mul_f32_e32 v161, v233, v161
	v_mul_f32_e32 v162, v233, v162
	v_mul_f32_e32 v163, v233, v163
	v_mul_f32_e32 v164, v233, v164
	v_mul_f32_e32 v165, v233, v165
	v_mul_f32_e32 v166, v233, v166
	v_mul_f32_e32 v167, v233, v167
	v_mul_f32_e32 v168, v233, v168
	v_mul_f32_e32 v169, v233, v169
	v_mul_f32_e32 v170, v233, v170
	v_mul_f32_e32 v171, v233, v171
	v_mul_f32_e32 v172, v233, v172
	v_mul_f32_e32 v173, v233, v173
	v_mul_f32_e32 v174, v233, v174
	v_mul_f32_e32 v175, v233, v175
	v_mul_f32_e32 v176, v233, v176
	v_mul_f32_e32 v177, v233, v177
	v_cvt_pk_bf16_f32 v130, v130, v131
	v_cvt_pk_bf16_f32 v131, v132, v133
	v_cvt_pk_bf16_f32 v132, v134, v135
	v_cvt_pk_bf16_f32 v133, v136, v137
	v_cvt_pk_bf16_f32 v134, v138, v139
	v_cvt_pk_bf16_f32 v135, v140, v141
	v_cvt_pk_bf16_f32 v136, v142, v143
	v_cvt_pk_bf16_f32 v137, v144, v145
	s_waitcnt lgkmcnt(0)
	s_nop 1
	v_mfma_f32_32x32x16_bf16 v[146:161], v[178:181], v[130:133], v[146:161]
	v_mfma_f32_32x32x16_bf16 v[162:177], v[182:185], v[130:133], v[162:177]
	v_mfma_f32_32x32x16_bf16 v[146:161], v[186:189], v[134:137], v[146:161]
	v_mfma_f32_32x32x16_bf16 v[162:177], v[190:193], v[134:137], v[162:177]
	s_branch .Lattn_end2
.Lattn_skip2:
	v_add_u32_e32 v246, 0xffffffc0, v231
	v_max_i32_e32 v246, 0, v246
	v_lshlrev_b32_e32 v246, s10, v246
	v_add_u32_e32 v246, s11, v246
	v_mul_u32_u24_e32 v246, 0x2400, v246
	v_add_u32_e32 v246, v246, v240
	global_load_dwordx4 v[34:37], v246, s[8:9] offset:0
	global_load_dwordx4 v[38:41], v246, s[8:9] offset:32
	global_load_dwordx4 v[42:45], v246, s[8:9] offset:64
	global_load_dwordx4 v[46:49], v246, s[8:9] offset:96
.Lattn_end2:
	s_bitcmp1_b32 s2, 3
	s_cbranch_scc1 .Lattn_skip3
	v_mfma_f32_32x32x16_bf16 v[130:145], v[50:53], v[82:85], 0
	v_mfma_f32_32x32x16_bf16 v[130:145], v[54:57], v[86:89], v[130:145]
	v_mfma_f32_32x32x16_bf16 v[130:145], v[58:61], v[90:93], v[130:145]
	v_mfma_f32_32x32x16_bf16 v[130:145], v[62:65], v[94:97], v[130:145]
	v_add_u32_e32 v246, 0xffffffe0, v231
	v_max_i32_e32 v246, 0, v246
	v_lshlrev_b32_e32 v246, s10, v246
	v_add_u32_e32 v246, s11, v246
	v_mul_u32_u24_e32 v246, 0x2400, v246
	v_add_u32_e32 v246, v246, v240
	global_load_dwordx4 v[50:53], v246, s[8:9] offset:0
	global_load_dwordx4 v[54:57], v246, s[8:9] offset:32
	global_load_dwordx4 v[58:61], v246, s[8:9] offset:64
	global_load_dwordx4 v[62:65], v246, s[8:9] offset:96
	ds_read2_b32 v[178:179], v222 offset0:63 offset1:62
	ds_read2_b32 v[180:181], v222 offset0:61 offset1:60
	ds_read2_b32 v[182:183], v222 offset0:55 offset1:54
	ds_read2_b32 v[184:185], v222 offset0:53 offset1:52
	ds_read2_b32 v[186:187], v222 offset0:47 offset1:46
	ds_read2_b32 v[188:189], v222 offset0:45 offset1:44
	ds_read2_b32 v[190:191], v222 offset0:39 offset1:38
	ds_read2_b32 v[192:193], v222 offset0:37 offset1:36
	s_waitcnt lgkmcnt(0)
; DI void phase_attn_a(int wv_, int vb_, int nvb_, char* ws_, const Ctx& p, char* smem) {
;     ...
;       for (int kb = 0; kb < 5; ++kb) {
;         const int kk = 32 * wave + 32 * kb + c; const int ksub0 = nb * 128 - 128 + kk;
;         bf16x8 kf[4];
;         if (ksub0 >= 0) {
;           const u16* kp = P + ((size_t)b * SEQ + (size_t)ksub0 * dil + r) * 4608 + 1536 + g * 512 + head * 64;
; #pragma unroll
;           for (int ks = 0; ks < 4; ++ks) kf[ks] = *(const bf16x8*)(kp + ks * 16 + h * 8);
;         } else {
; #pragma unroll
;           for (int ks = 0; ks < 4; ++ks) kf[ks] = zero8();
;         }
;         f32x16 sa = zero16();
; #pragma unroll
;         for (int ks = 0; ks < 4; ++ks) sa = MFMA32(kf[ks], qf[ks], sa);
;         float bm = -INFINITY;
;         const int sbase = c + 128 - 32 * kb - 4 * h;
;         const unsigned slim = (unsigned)((nb * 128 + 32 * wave + c) < 128 ? (nb * 128 + 32 * wave + c) : 128);
;         if (nb > 0 && kb >= 1 && kb <= 3) {
; #pragma unroll
;           for (int i = 0; i < 16; ++i) {
;             const int step = sbase - ((i & 3) + 8 * (i >> 2));
;             const float v = sa[i] + sBias[step];
;             sa[i] = v; bm = fmaxf(bm, v);
;           }
;         } else {
; #pragma unroll
;           for (int i = 0; i < 16; ++i) {
;             const int step = sbase - ((i & 3) + 8 * (i >> 2));
;             const bool valid = (unsigned)step <= slim;
;             const float bv = sBias[step];
;             float v = valid ? sa[i] + bv : -INFINITY;
;             sa[i] = v; bm = fmaxf(bm, v);
;           }
;         }
;         bm = fmaxf(bm, shx(bm, 32));
;         const float mnew = fmaxf(mx, bm);
;         const float mref = (mnew == -INFINITY) ? 0.f : mnew;
;         const float scale = __builtin_amdgcn_exp2f(mx - mref);
;         float ps = 0.f;
; #pragma unroll
;         for (int i = 0; i < 16; ++i) { float pv = __builtin_amdgcn_exp2f(sa[i] - mref); sa[i] = pv; ps += pv; }
;         sum = sum * scale + ps; mx = mnew;
; #pragma unroll
;         for (int i = 0; i < 16; ++i) { oacc[0][i] *= scale; oacc[1][i] *= scale; }
; #pragma unroll
;         for (int s = 0; s < 2; ++s) {
;           bf16x8 pb = pack8(sa, s);
;           const int keybase = 32 * wave + 32 * kb + 16 * s;
; #pragma unroll
;           for (int mb = 0; mb < 2; ++mb) {
;             const u16* vr = Vt + (mb * 32 + c) * 260 + keybase + 4 * h;
	v_add_f32_e32 v130, v130, v178
	v_add_f32_e32 v131, v131, v179
	v_add_f32_e32 v132, v132, v180
	v_add_f32_e32 v133, v133, v181
	v_add_f32_e32 v134, v134, v182
	v_add_f32_e32 v135, v135, v183
	v_add_f32_e32 v136, v136, v184
	v_add_f32_e32 v137, v137, v185
	v_add_f32_e32 v138, v138, v186
	v_add_f32_e32 v139, v139, v187
	v_add_f32_e32 v140, v140, v188
	v_add_f32_e32 v141, v141, v189
	v_add_f32_e32 v142, v142, v190
	v_add_f32_e32 v143, v143, v191
	v_add_f32_e32 v144, v144, v192
	v_add_f32_e32 v145, v145, v193
	ds_read_b64 v[178:179], v221 offset:192
	ds_read_b64 v[180:181], v221 offset:208
	ds_read_b64 v[182:183], v221 offset:16832
	ds_read_b64 v[184:185], v221 offset:16848
	ds_read_b64 v[186:187], v221 offset:224
	ds_read_b64 v[188:189], v221 offset:240
	ds_read_b64 v[190:191], v221 offset:16864
	ds_read_b64 v[192:193], v221 offset:16880
	v_max3_f32 v235, v130, v131, v132
	v_max3_f32 v235, v235, v133, v134
	v_max3_f32 v235, v235, v135, v136
	v_max3_f32 v235, v235, v137, v138
	v_max3_f32 v235, v235, v139, v140
	v_max3_f32 v235, v235, v141, v142
	v_max3_f32 v235, v235, v143, v144
	v_max_f32_e32 v235, v235, v145
	v_mov_b32_e32 v196, v235
	s_nop 1
	v_permlane32_swap_b32_e32 v196, v235
	v_max_f32_e32 v235, v235, v196
	v_max_f32_e32 v234, v194, v235
	v_cmp_eq_f32_e32 vcc, 0xff800000, v234
	s_nop 1
	v_cndmask_b32_e64 v237, v234, 0, vcc
	v_sub_f32_e32 v196, v194, v237
	v_exp_f32_e32 v233, v196
	v_sub_f32_e32 v130, v130, v237
	v_sub_f32_e32 v131, v131, v237
	v_sub_f32_e32 v132, v132, v237
	v_sub_f32_e32 v133, v133, v237
	v_sub_f32_e32 v134, v134, v237
	v_sub_f32_e32 v135, v135, v237
	v_sub_f32_e32 v136, v136, v237
	v_sub_f32_e32 v137, v137, v237
	v_sub_f32_e32 v138, v138, v237
	v_sub_f32_e32 v139, v139, v237
	v_sub_f32_e32 v140, v140, v237
	v_sub_f32_e32 v141, v141, v237
	v_sub_f32_e32 v142, v142, v237
	v_sub_f32_e32 v143, v143, v237
	v_sub_f32_e32 v144, v144, v237
	v_sub_f32_e32 v145, v145, v237
	v_exp_f32_e32 v130, v130
	v_exp_f32_e32 v131, v131
	v_exp_f32_e32 v132, v132
	v_exp_f32_e32 v133, v133
	v_exp_f32_e32 v134, v134
	v_exp_f32_e32 v135, v135
	v_exp_f32_e32 v136, v136
	v_exp_f32_e32 v137, v137
	v_exp_f32_e32 v138, v138
	v_exp_f32_e32 v139, v139
	v_exp_f32_e32 v140, v140
	v_exp_f32_e32 v141, v141
	v_exp_f32_e32 v142, v142
	v_exp_f32_e32 v143, v143
	v_exp_f32_e32 v144, v144
	v_exp_f32_e32 v145, v145
	v_mov_b32_e32 v194, v234
	v_add_f32_e32 v236, v130, v131
	v_add_f32_e32 v236, v236, v132
	v_add_f32_e32 v236, v236, v133
	v_add_f32_e32 v236, v236, v134
	v_add_f32_e32 v236, v236, v135
	v_add_f32_e32 v236, v236, v136
	v_add_f32_e32 v236, v236, v137
	v_add_f32_e32 v236, v236, v138
	v_add_f32_e32 v236, v236, v139
	v_add_f32_e32 v236, v236, v140
	v_add_f32_e32 v236, v236, v141
	v_add_f32_e32 v236, v236, v142
	v_add_f32_e32 v236, v236, v143
	v_add_f32_e32 v236, v236, v144
	v_add_f32_e32 v236, v236, v145
	v_fma_f32 v195, v195, v233, v236
	v_mul_f32_e32 v146, v233, v146
	v_mul_f32_e32 v147, v233, v147
	v_mul_f32_e32 v148, v233, v148
	v_mul_f32_e32 v149, v233, v149
	v_mul_f32_e32 v150, v233, v150
	v_mul_f32_e32 v151, v233, v151
	v_mul_f32_e32 v152, v233, v152
	v_mul_f32_e32 v153, v233, v153
	v_mul_f32_e32 v154, v233, v154
	v_mul_f32_e32 v155, v233, v155
	v_mul_f32_e32 v156, v233, v156
	v_mul_f32_e32 v157, v233, v157
	v_mul_f32_e32 v158, v233, v158
	v_mul_f32_e32 v159, v233, v159
	v_mul_f32_e32 v160, v233, v160
	v_mul_f32_e32 v161, v233, v161
	v_mul_f32_e32 v162, v233, v162
	v_mul_f32_e32 v163, v233, v163
	v_mul_f32_e32 v164, v233, v164
	v_mul_f32_e32 v165, v233, v165
	v_mul_f32_e32 v166, v233, v166
	v_mul_f32_e32 v167, v233, v167
	v_mul_f32_e32 v168, v233, v168
	v_mul_f32_e32 v169, v233, v169
	v_mul_f32_e32 v170, v233, v170
	v_mul_f32_e32 v171, v233, v171
	v_mul_f32_e32 v172, v233, v172
	v_mul_f32_e32 v173, v233, v173
	v_mul_f32_e32 v174, v233, v174
	v_mul_f32_e32 v175, v233, v175
	v_mul_f32_e32 v176, v233, v176
	v_mul_f32_e32 v177, v233, v177
	v_cvt_pk_bf16_f32 v130, v130, v131
	v_cvt_pk_bf16_f32 v131, v132, v133
	v_cvt_pk_bf16_f32 v132, v134, v135
	v_cvt_pk_bf16_f32 v133, v136, v137
	v_cvt_pk_bf16_f32 v134, v138, v139
	v_cvt_pk_bf16_f32 v135, v140, v141
	v_cvt_pk_bf16_f32 v136, v142, v143
	v_cvt_pk_bf16_f32 v137, v144, v145
	s_waitcnt lgkmcnt(0)
	s_nop 1
	v_mfma_f32_32x32x16_bf16 v[146:161], v[178:181], v[130:133], v[146:161]
	v_mfma_f32_32x32x16_bf16 v[162:177], v[182:185], v[130:133], v[162:177]
	v_mfma_f32_32x32x16_bf16 v[146:161], v[186:189], v[134:137], v[146:161]
	v_mfma_f32_32x32x16_bf16 v[162:177], v[190:193], v[134:137], v[162:177]
	s_branch .Lattn_end3
.Lattn_skip3:
	v_add_u32_e32 v246, 0xffffffe0, v231
	v_max_i32_e32 v246, 0, v246
	v_lshlrev_b32_e32 v246, s10, v246
	v_add_u32_e32 v246, s11, v246
	v_mul_u32_u24_e32 v246, 0x2400, v246
	v_add_u32_e32 v246, v246, v240
	global_load_dwordx4 v[50:53], v246, s[8:9] offset:0
	global_load_dwordx4 v[54:57], v246, s[8:9] offset:32
	global_load_dwordx4 v[58:61], v246, s[8:9] offset:64
	global_load_dwordx4 v[62:65], v246, s[8:9] offset:96
; DI void phase_attn_a(int wv_, int vb_, int nvb_, char* ws_, const Ctx& p, char* smem) {
;     ...
;       for (int kb = 0; kb < 5; ++kb) {
;         const int kk = 32 * wave + 32 * kb + c; const int ksub0 = nb * 128 - 128 + kk;
;         bf16x8 kf[4];
;         if (ksub0 >= 0) {
;           const u16* kp = P + ((size_t)b * SEQ + (size_t)ksub0 * dil + r) * 4608 + 1536 + g * 512 + head * 64;
; #pragma unroll
;           for (int ks = 0; ks < 4; ++ks) kf[ks] = *(const bf16x8*)(kp + ks * 16 + h * 8);
;         } else {
; #pragma unroll
;           for (int ks = 0; ks < 4; ++ks) kf[ks] = zero8();
;         }
;         f32x16 sa = zero16();
; #pragma unroll
;         for (int ks = 0; ks < 4; ++ks) sa = MFMA32(kf[ks], qf[ks], sa);
;         float bm = -INFINITY;
;         const int sbase = c + 128 - 32 * kb - 4 * h;
;         const unsigned slim = (unsigned)((nb * 128 + 32 * wave + c) < 128 ? (nb * 128 + 32 * wave + c) : 128);
;         if (nb > 0 && kb >= 1 && kb <= 3) {
; #pragma unroll
;           for (int i = 0; i < 16; ++i) {
;             const int step = sbase - ((i & 3) + 8 * (i >> 2));
;             const float v = sa[i] + sBias[step];
;             sa[i] = v; bm = fmaxf(bm, v);
;           }
;         } else {
; #pragma unroll
;           for (int i = 0; i < 16; ++i) {
;             const int step = sbase - ((i & 3) + 8 * (i >> 2));
;             const bool valid = (unsigned)step <= slim;
;             const float bv = sBias[step];
;             float v = valid ? sa[i] + bv : -INFINITY;
;             sa[i] = v; bm = fmaxf(bm, v);
;           }
;         }
;         bm = fmaxf(bm, shx(bm, 32));
;         const float mnew = fmaxf(mx, bm);
;         const float mref = (mnew == -INFINITY) ? 0.f : mnew;
;         const float scale = __builtin_amdgcn_exp2f(mx - mref);
;         float ps = 0.f;
; #pragma unroll
;         for (int i = 0; i < 16; ++i) { float pv = __builtin_amdgcn_exp2f(sa[i] - mref); sa[i] = pv; ps += pv; }
;         sum = sum * scale + ps; mx = mnew;
; #pragma unroll
;         for (int i = 0; i < 16; ++i) { oacc[0][i] *= scale; oacc[1][i] *= scale; }
; #pragma unroll
;         for (int s = 0; s < 2; ++s) {
;           bf16x8 pb = pack8(sa, s);
;           const int keybase = 32 * wave + 32 * kb + 16 * s;
; #pragma unroll
;           for (int mb = 0; mb < 2; ++mb) {
;             const u16* vr = Vt + (mb * 32 + c) * 260 + keybase + 4 * h;
.Lattn_end3:
	s_bitcmp1_b32 s2, 4
	s_cbranch_scc1 .Lattn_skip4
	v_mfma_f32_32x32x16_bf16 v[130:145], v[66:69], v[82:85], 0
	v_mfma_f32_32x32x16_bf16 v[130:145], v[70:73], v[86:89], v[130:145]
	v_mfma_f32_32x32x16_bf16 v[130:145], v[74:77], v[90:93], v[130:145]
	v_mfma_f32_32x32x16_bf16 v[130:145], v[78:81], v[94:97], v[130:145]
	v_mov_b32_e32 v246, v231
	v_max_i32_e32 v246, 0, v246
	v_lshlrev_b32_e32 v246, s10, v246
	v_add_u32_e32 v246, s11, v246
	v_mul_u32_u24_e32 v246, 0x2400, v246
	v_add_u32_e32 v246, v246, v240
	global_load_dwordx4 v[66:69], v246, s[8:9] offset:0
	global_load_dwordx4 v[70:73], v246, s[8:9] offset:32
	global_load_dwordx4 v[74:77], v246, s[8:9] offset:64
	global_load_dwordx4 v[78:81], v246, s[8:9] offset:96
	global_load_dwordx4 v[82:85], v232, s[8:9] offset:0
	global_load_dwordx4 v[86:89], v232, s[8:9] offset:32
	global_load_dwordx4 v[90:93], v232, s[8:9] offset:64
	global_load_dwordx4 v[94:97], v232, s[8:9] offset:96
	ds_read2_b32 v[178:179], v222 offset0:31 offset1:30
	ds_read2_b32 v[180:181], v222 offset0:29 offset1:28
	ds_read2_b32 v[182:183], v222 offset0:23 offset1:22
	ds_read2_b32 v[184:185], v222 offset0:21 offset1:20
	ds_read2_b32 v[186:187], v222 offset0:15 offset1:14
	ds_read2_b32 v[188:189], v222 offset0:13 offset1:12
	ds_read2_b32 v[190:191], v222 offset0:7 offset1:6
	ds_read2_b32 v[192:193], v222 offset0:5 offset1:4
	s_waitcnt lgkmcnt(0)
	v_add_f32_e32 v130, v130, v178
	v_add_f32_e32 v131, v131, v179
	v_add_f32_e32 v132, v132, v180
	v_add_f32_e32 v133, v133, v181
	v_add_f32_e32 v134, v134, v182
	v_add_f32_e32 v135, v135, v183
	v_add_f32_e32 v136, v136, v184
	v_add_f32_e32 v137, v137, v185
	v_add_f32_e32 v138, v138, v186
	v_add_f32_e32 v139, v139, v187
	v_add_f32_e32 v140, v140, v188
	v_add_f32_e32 v141, v141, v189
	v_add_f32_e32 v142, v142, v190
	v_add_f32_e32 v143, v143, v191
	v_add_f32_e32 v144, v144, v192
	v_add_f32_e32 v145, v145, v193
	ds_read_b64 v[178:179], v221 offset:256
	ds_read_b64 v[180:181], v221 offset:272
	ds_read_b64 v[182:183], v221 offset:16896
	ds_read_b64 v[184:185], v221 offset:16912
	ds_read_b64 v[186:187], v221 offset:288
	ds_read_b64 v[188:189], v221 offset:304
	ds_read_b64 v[190:191], v221 offset:16928
	ds_read_b64 v[192:193], v221 offset:16944
	v_max3_f32 v235, v130, v131, v132
	v_max3_f32 v235, v235, v133, v134
	v_max3_f32 v235, v235, v135, v136
	v_max3_f32 v235, v235, v137, v138
	v_max3_f32 v235, v235, v139, v140
	v_max3_f32 v235, v235, v141, v142
	v_max3_f32 v235, v235, v143, v144
	v_max_f32_e32 v235, v235, v145
	v_mov_b32_e32 v196, v235
	s_nop 1
	v_permlane32_swap_b32_e32 v196, v235
	v_max_f32_e32 v235, v235, v196
	v_max_f32_e32 v234, v194, v235
	v_cmp_eq_f32_e32 vcc, 0xff800000, v234
	s_nop 1
	v_cndmask_b32_e64 v237, v234, 0, vcc
	v_sub_f32_e32 v196, v194, v237
	v_exp_f32_e32 v233, v196
	v_sub_f32_e32 v130, v130, v237
	v_sub_f32_e32 v131, v131, v237
	v_sub_f32_e32 v132, v132, v237
	v_sub_f32_e32 v133, v133, v237
	v_sub_f32_e32 v134, v134, v237
	v_sub_f32_e32 v135, v135, v237
	v_sub_f32_e32 v136, v136, v237
	v_sub_f32_e32 v137, v137, v237
	v_sub_f32_e32 v138, v138, v237
	v_sub_f32_e32 v139, v139, v237
	v_sub_f32_e32 v140, v140, v237
	v_sub_f32_e32 v141, v141, v237
	v_sub_f32_e32 v142, v142, v237
	v_sub_f32_e32 v143, v143, v237
	v_sub_f32_e32 v144, v144, v237
	v_sub_f32_e32 v145, v145, v237
	v_exp_f32_e32 v130, v130
	v_exp_f32_e32 v131, v131
	v_exp_f32_e32 v132, v132
	v_exp_f32_e32 v133, v133
	v_exp_f32_e32 v134, v134
	v_exp_f32_e32 v135, v135
	v_exp_f32_e32 v136, v136
	v_exp_f32_e32 v137, v137
	v_exp_f32_e32 v138, v138
	v_exp_f32_e32 v139, v139
	v_exp_f32_e32 v140, v140
	v_exp_f32_e32 v141, v141
	v_exp_f32_e32 v142, v142
	v_exp_f32_e32 v143, v143
	v_exp_f32_e32 v144, v144
	v_exp_f32_e32 v145, v145
	v_mov_b32_e32 v194, v234
	v_add_f32_e32 v236, v130, v131
	v_add_f32_e32 v236, v236, v132
	v_add_f32_e32 v236, v236, v133
	v_add_f32_e32 v236, v236, v134
	v_add_f32_e32 v236, v236, v135
	v_add_f32_e32 v236, v236, v136
	v_add_f32_e32 v236, v236, v137
	v_add_f32_e32 v236, v236, v138
	v_add_f32_e32 v236, v236, v139
	v_add_f32_e32 v236, v236, v140
	v_add_f32_e32 v236, v236, v141
	v_add_f32_e32 v236, v236, v142
	v_add_f32_e32 v236, v236, v143
	v_add_f32_e32 v236, v236, v144
	v_add_f32_e32 v236, v236, v145
	v_fma_f32 v195, v195, v233, v236
	v_mul_f32_e32 v146, v233, v146
	v_mul_f32_e32 v147, v233, v147
	v_mul_f32_e32 v148, v233, v148
	v_mul_f32_e32 v149, v233, v149
	v_mul_f32_e32 v150, v233, v150
	v_mul_f32_e32 v151, v233, v151
	v_mul_f32_e32 v152, v233, v152
	v_mul_f32_e32 v153, v233, v153
	v_mul_f32_e32 v154, v233, v154
	v_mul_f32_e32 v155, v233, v155
	v_mul_f32_e32 v156, v233, v156
	v_mul_f32_e32 v157, v233, v157
	v_mul_f32_e32 v158, v233, v158
	v_mul_f32_e32 v159, v233, v159
	v_mul_f32_e32 v160, v233, v160
	v_mul_f32_e32 v161, v233, v161
	v_mul_f32_e32 v162, v233, v162
	v_mul_f32_e32 v163, v233, v163
	v_mul_f32_e32 v164, v233, v164
	v_mul_f32_e32 v165, v233, v165
	v_mul_f32_e32 v166, v233, v166
	v_mul_f32_e32 v167, v233, v167
	v_mul_f32_e32 v168, v233, v168
	v_mul_f32_e32 v169, v233, v169
	v_mul_f32_e32 v170, v233, v170
	v_mul_f32_e32 v171, v233, v171
	v_mul_f32_e32 v172, v233, v172
	v_mul_f32_e32 v173, v233, v173
	v_mul_f32_e32 v174, v233, v174
	v_mul_f32_e32 v175, v233, v175
	v_mul_f32_e32 v176, v233, v176
	v_mul_f32_e32 v177, v233, v177
	v_cvt_pk_bf16_f32 v130, v130, v131
	v_cvt_pk_bf16_f32 v131, v132, v133
	v_cvt_pk_bf16_f32 v132, v134, v135
	v_cvt_pk_bf16_f32 v133, v136, v137
	v_cvt_pk_bf16_f32 v134, v138, v139
	v_cvt_pk_bf16_f32 v135, v140, v141
	v_cvt_pk_bf16_f32 v136, v142, v143
	v_cvt_pk_bf16_f32 v137, v144, v145
	s_waitcnt lgkmcnt(0)
	s_nop 1
	v_mfma_f32_32x32x16_bf16 v[146:161], v[178:181], v[130:133], v[146:161]
	v_mfma_f32_32x32x16_bf16 v[162:177], v[182:185], v[130:133], v[162:177]
	v_mfma_f32_32x32x16_bf16 v[146:161], v[186:189], v[134:137], v[146:161]
	v_mfma_f32_32x32x16_bf16 v[162:177], v[190:193], v[134:137], v[162:177]
	s_branch .Lattn_end4
; DI float shx(float v, int m) { return __int_as_float(__builtin_amdgcn_ds_bpermute((lane_now() ^ m) << 2, __float_as_int(v))); }
; DI int shx(int v, int m) { return __builtin_amdgcn_ds_bpermute((lane_now() ^ m) << 2, v); }
; DI u16 f2bf(float x) { return (u16)(pk2bf(x, 0.f) & 0xffffu); }
; DI void phase_attn_a(int wv_, int vb_, int nvb_, char* ws_, const Ctx& p, char* smem) {
;     ...
;       const int kk = tid; const int ksub = nb * 128 - 128 + kk;
;       bf16x8 v[8];
;       if (ksub >= 0) {
;         const u16* vp = P + ((size_t)b * SEQ + (size_t)ksub * dil + r) * 4608 + 3072 + g * 512 + head * 64;
; #pragma unroll
;         for (int i = 0; i < 8; ++i) v[i] = *(const bf16x8*)(vp + i * 8);
;       } else {
; #pragma unroll
;         for (int i = 0; i < 8; ++i) v[i] = zero8();
;       }
; #pragma unroll
;       for (int i = 0; i < 8; ++i)
; #pragma unroll
;         for (int jj = 0; jj < 8; ++jj) Vt[(i * 8 + jj) * 260 + kk] = (u16)v[i][jj];
;     }
;     __syncthreads();
;     ...
;       sum += shx(sum, 32);
;       const float inv = 1.0f / sum;
;       u16* op = Og + ((size_t)b * SEQ + qtok) * 512 + head * 64;
; #pragma unroll
;       for (int mb = 0; mb < 2; ++mb)
; #pragma unroll
;         for (int ig = 0; ig < 4; ++ig) {
;           s16x4 o;
; #pragma unroll
;           for (int q = 0; q < 4; ++q) o[q] = (short)f2bf(oacc[mb][ig * 4 + q] * inv);
;           *(s16x4*)(op + mb * 32 + 8 * ig + 4 * h) = o;
;         }
;       if (h == 0) lse[((size_t)b * SEQ + qtok) * 8 + head] = (mx + log2f(sum)) * 0.6931471805599453f;
;     }
;     __syncthreads();
.Lattn_skip4:
	v_mov_b32_e32 v246, v231
	v_max_i32_e32 v246, 0, v246
	v_lshlrev_b32_e32 v246, s10, v246
	v_add_u32_e32 v246, s11, v246
	v_mul_u32_u24_e32 v246, 0x2400, v246
	v_add_u32_e32 v246, v246, v240
	global_load_dwordx4 v[66:69], v246, s[8:9] offset:0
	global_load_dwordx4 v[70:73], v246, s[8:9] offset:32
	global_load_dwordx4 v[74:77], v246, s[8:9] offset:64
	global_load_dwordx4 v[78:81], v246, s[8:9] offset:96
	global_load_dwordx4 v[82:85], v232, s[8:9] offset:0
	global_load_dwordx4 v[86:89], v232, s[8:9] offset:32
	global_load_dwordx4 v[90:93], v232, s[8:9] offset:64
	global_load_dwordx4 v[94:97], v232, s[8:9] offset:96
.Lattn_end4:
	s_waitcnt vmcnt(24)
	ds_write_b16 v223, v98
	ds_write_b16_d16_hi v223, v98 offset:520
	ds_write_b16 v223, v99 offset:1040
	ds_write_b16_d16_hi v223, v99 offset:1560
	ds_write_b16 v223, v100 offset:2080
	ds_write_b16_d16_hi v223, v100 offset:2600
	ds_write_b16 v223, v101 offset:3120
	ds_write_b16_d16_hi v223, v101 offset:3640
	ds_write_b16 v223, v102 offset:4160
	ds_write_b16_d16_hi v223, v102 offset:4680
	ds_write_b16 v223, v103 offset:5200
	ds_write_b16_d16_hi v223, v103 offset:5720
	ds_write_b16 v223, v104 offset:6240
	ds_write_b16_d16_hi v223, v104 offset:6760
	ds_write_b16 v223, v105 offset:7280
	ds_write_b16_d16_hi v223, v105 offset:7800
	ds_write_b16 v223, v106 offset:8320
	ds_write_b16_d16_hi v223, v106 offset:8840
	ds_write_b16 v223, v107 offset:9360
	ds_write_b16_d16_hi v223, v107 offset:9880
	ds_write_b16 v223, v108 offset:10400
	ds_write_b16_d16_hi v223, v108 offset:10920
	ds_write_b16 v223, v109 offset:11440
	ds_write_b16_d16_hi v223, v109 offset:11960
	ds_write_b16 v223, v110 offset:12480
	ds_write_b16_d16_hi v223, v110 offset:13000
	ds_write_b16 v223, v111 offset:13520
	ds_write_b16_d16_hi v223, v111 offset:14040
	ds_write_b16 v223, v112 offset:14560
	ds_write_b16_d16_hi v223, v112 offset:15080
	ds_write_b16 v223, v113 offset:15600
	ds_write_b16_d16_hi v223, v113 offset:16120
	ds_write_b16 v223, v114 offset:16640
	ds_write_b16_d16_hi v223, v114 offset:17160
	ds_write_b16 v223, v115 offset:17680
	ds_write_b16_d16_hi v223, v115 offset:18200
	ds_write_b16 v223, v116 offset:18720
	ds_write_b16_d16_hi v223, v116 offset:19240
	ds_write_b16 v223, v117 offset:19760
	ds_write_b16_d16_hi v223, v117 offset:20280
	ds_write_b16 v223, v118 offset:20800
	ds_write_b16_d16_hi v223, v118 offset:21320
	ds_write_b16 v223, v119 offset:21840
	ds_write_b16_d16_hi v223, v119 offset:22360
	ds_write_b16 v223, v120 offset:22880
	ds_write_b16_d16_hi v223, v120 offset:23400
	ds_write_b16 v223, v121 offset:23920
	ds_write_b16_d16_hi v223, v121 offset:24440
	ds_write_b16 v223, v122 offset:24960
	ds_write_b16_d16_hi v223, v122 offset:25480
	ds_write_b16 v223, v123 offset:26000
	ds_write_b16_d16_hi v223, v123 offset:26520
	ds_write_b16 v223, v124 offset:27040
	ds_write_b16_d16_hi v223, v124 offset:27560
	ds_write_b16 v223, v125 offset:28080
	ds_write_b16_d16_hi v223, v125 offset:28600
	ds_write_b16 v223, v126 offset:29120
	ds_write_b16_d16_hi v223, v126 offset:29640
	ds_write_b16 v223, v127 offset:30160
	ds_write_b16_d16_hi v223, v127 offset:30680
	ds_write_b16 v223, v128 offset:31200
	ds_write_b16_d16_hi v223, v128 offset:31720
	ds_write_b16 v223, v129 offset:32240
	ds_write_b16_d16_hi v223, v129 offset:32760
	v_mul_f32_e32 v196, 0x3fb8aa3b, v229
	v_cndmask_b32_e64 v196, v207, v196, s[66:67]
	ds_write_b32 v224, v196
	v_mov_b32_e32 v196, v195
	s_nop 1
	v_permlane32_swap_b32_e32 v196, v195
	v_add_f32_e32 v195, v195, v196
	v_rcp_f32_e32 v238, v195
	v_log_f32_e32 v197, v195
	s_nop 0
	v_mul_f32_e32 v146, v238, v146
	v_mul_f32_e32 v147, v238, v147
	v_mul_f32_e32 v148, v238, v148
	v_mul_f32_e32 v149, v238, v149
	v_mul_f32_e32 v150, v238, v150
	v_mul_f32_e32 v151, v238, v151
	v_mul_f32_e32 v152, v238, v152
	v_mul_f32_e32 v153, v238, v153
	v_mul_f32_e32 v154, v238, v154
	v_mul_f32_e32 v155, v238, v155
	v_mul_f32_e32 v156, v238, v156
	v_mul_f32_e32 v157, v238, v157
	v_mul_f32_e32 v158, v238, v158
	v_mul_f32_e32 v159, v238, v159
	v_mul_f32_e32 v160, v238, v160
	v_mul_f32_e32 v161, v238, v161
	v_mul_f32_e32 v162, v238, v162
	v_mul_f32_e32 v163, v238, v163
	v_mul_f32_e32 v164, v238, v164
	v_mul_f32_e32 v165, v238, v165
	v_mul_f32_e32 v166, v238, v166
	v_mul_f32_e32 v167, v238, v167
	v_mul_f32_e32 v168, v238, v168
	v_mul_f32_e32 v169, v238, v169
	v_mul_f32_e32 v170, v238, v170
	v_mul_f32_e32 v171, v238, v171
	v_mul_f32_e32 v172, v238, v172
	v_mul_f32_e32 v173, v238, v173
	v_mul_f32_e32 v174, v238, v174
	v_mul_f32_e32 v175, v238, v175
	v_mul_f32_e32 v176, v238, v176
	v_mul_f32_e32 v177, v238, v177
	v_cvt_pk_bf16_f32 v146, v146, v147
	v_cvt_pk_bf16_f32 v147, v148, v149
	v_cvt_pk_bf16_f32 v150, v150, v151
	v_cvt_pk_bf16_f32 v151, v152, v153
	v_cvt_pk_bf16_f32 v154, v154, v155
	v_cvt_pk_bf16_f32 v155, v156, v157
	v_cvt_pk_bf16_f32 v158, v158, v159
	v_cvt_pk_bf16_f32 v159, v160, v161
	v_cvt_pk_bf16_f32 v162, v162, v163
	v_cvt_pk_bf16_f32 v163, v164, v165
	v_cvt_pk_bf16_f32 v166, v166, v167
	v_cvt_pk_bf16_f32 v167, v168, v169
	v_cvt_pk_bf16_f32 v170, v170, v171
	v_cvt_pk_bf16_f32 v171, v172, v173
	v_cvt_pk_bf16_f32 v174, v174, v175
	v_cvt_pk_bf16_f32 v175, v176, v177
	global_store_dwordx2 v225, v[146:147], s[4:5]
	global_store_dwordx2 v225, v[150:151], s[4:5] offset:16
	global_store_dwordx2 v225, v[154:155], s[4:5] offset:32
	global_store_dwordx2 v225, v[158:159], s[4:5] offset:48
	global_store_dwordx2 v225, v[162:163], s[4:5] offset:64
	global_store_dwordx2 v225, v[166:167], s[4:5] offset:80
	global_store_dwordx2 v225, v[170:171], s[4:5] offset:96
	global_store_dwordx2 v225, v[174:175], s[4:5] offset:112
	v_add_f32_e32 v197, v194, v197
	v_mul_f32_e32 v197, 0x3f317218, v197
	s_mov_b32 exec_hi, 0
	global_store_dword v227, v197, s[6:7]
	s_mov_b32 exec_hi, -1
	s_waitcnt lgkmcnt(0)
	s_barrier
	s_mov_b32 s2, s13
	s_mov_b64 s[4:5], s[14:15]
	s_mov_b64 s[6:7], s[18:19]
	v_mov_b32_e32 v225, v226
	v_mov_b32_e32 v227, v228
	v_add_u32_e32 v221, s64, v209
	v_add_u32_e32 v222, s65, v216
	s_sub_i32 s64, 0x8200, s64
	s_sub_i32 s65, 0x400, s65
	s_add_i32 s34, s34, 1
	s_cmp_lt_i32 s34, s35
	s_cbranch_scc1 .Lattn_loop
	s_waitcnt vmcnt(0)
